# stack6: + residual epilogues issue both column-half residual-stream loads of a 16-row group together (8 instead of 16 serialized round trips per tile)
# baseline (speedup 1.0000x reference)
; DI unsigned pk2(float lo, float hi) { f32x2_t v = {lo, hi}; bf16x2_t b = __builtin_convertvector(v, bf16x2_t); return __builtin_bit_cast(unsigned, b); }
; DI float bflo(unsigned u) { return __uint_as_float(u << 16); }
; DI float bfhi(unsigned u) { return __uint_as_float(u & 0xffff0000u); }
;     DI void operator()(pg8::f32x4 (&acc)[2][2][4][2], const pg8::Unit& u, int wr, int wc, int fr, int fq) const {
;     ...
;         const int colb = u.pn * 256 + wc * 32 + 8 * fq;
; #pragma unroll
;         for (int ai = 0; ai < 2; ++ai)
; #pragma unroll
;             for (int m = 0; m < 4; ++m) {
;                 const int rl = ai * 128 + wr * 64 + m * 16 + fr; const float r1 = S[rl];
;                 const size_t ro = (size_t)(u.pm * 256 + rl) * 1024 + colb;
;                 float q = 0.f;
; #pragma unroll
;                 for (int bj = 0; bj < 2; ++bj) {
;                     const v4u xw = *(const v4u*)(XB + ro + bj * 128);
;                     const v4f g0 = *(const v4f*)(gpost + colb + bj * 128), g1 = *(const v4f*)(gpost + colb + bj * 128 + 4);
;                     const pg8::f32x4 a0 = acc[ai][bj][m][0], a1 = acc[ai][bj][m][1];
;                     float v[8];
;                     v[0] = bflo(xw.x) + a0[0] * r1 * g0[0]; v[1] = bfhi(xw.x) + a0[1] * r1 * g0[1]; v[2] = bflo(xw.y) + a0[2] * r1 * g0[2]; v[3] = bfhi(xw.y) + a0[3] * r1 * g0[3];
;                     v[4] = bflo(xw.z) + a1[0] * r1 * g1[0]; v[5] = bfhi(xw.z) + a1[1] * r1 * g1[1]; v[6] = bflo(xw.w) + a1[2] * r1 * g1[2]; v[7] = bfhi(xw.w) + a1[3] * r1 * g1[3];
;                     q += ((v[0] * v[0] + v[1] * v[1]) + (v[2] * v[2] + v[3] * v[3])) + ((v[4] * v[4] + v[5] * v[5]) + (v[6] * v[6] + v[7] * v[7]));
;                     if (last) { *(v4f*)(OUT + ro + bj * 128) = (v4f){v[0], v[1], v[2], v[3]}; *(v4f*)(OUT + ro + bj * 128 + 4) = (v4f){v[4], v[5], v[6], v[7]}; }
;                     else { v4u w; w.x = pk2(v[0], v[1]); w.y = pk2(v[2], v[3]); w.z = pk2(v[4], v[5]); w.w = pk2(v[6], v[7]); *(v4u*)(XB + ro + bj * 128) = w; }
.LBB0_132:
	s_or_b64 exec, exec, s[26:27]
	v_readlane_b32 s0, v255, 7
	v_readlane_b32 s1, v255, 8
	s_lshl_b64 s[22:23], s[0:1], 2
	s_add_u32 s26, s48, s22
	v_add_u32_e32 v134, v152, v158
	s_addc_u32 s27, s49, s23
	v_lshl_or_b32 v132, s8, 8, v160
	s_waitcnt lgkmcnt(0)
	v_ashrrev_i32_e32 v135, 31, v134
	s_add_u32 s22, s24, 0x7000000
	v_ashrrev_i32_e32 v133, 31, v132
	v_lshlrev_b64 v[136:137], 10, v[134:135]
	s_addc_u32 s23, s25, 0
	v_lshl_add_u64 v[150:151], v[136:137], 0, v[132:133]
	s_waitcnt lgkmcnt(0)
	s_barrier
	v_lshl_add_u64 v[136:137], v[150:151], 1, s[22:23]
	v_lshl_add_u64 v[130:131], v[132:133], 2, s[26:27]
	ds_read_b32 v148, v169
	global_load_dwordx4 v[154:157], v[136:137], off
	global_load_dwordx4 v[206:209], v[136:137], off offset:256
	global_load_dwordx4 v[182:185], v[130:131], off offset:16
	global_load_dwordx4 v[186:189], v[130:131], off
	s_mov_b64 s[26:27], -1
	s_and_b64 vcc, exec, s[18:19]
	s_waitcnt lgkmcnt(0)
	v_pk_mul_f32 v[128:129], v[128:129], v[148:149] op_sel_hi:[1,0]
	v_pk_mul_f32 v[122:123], v[122:123], v[148:149] op_sel_hi:[1,0]
	v_pk_mul_f32 v[126:127], v[126:127], v[148:149] op_sel_hi:[1,0]
	v_pk_mul_f32 v[124:125], v[124:125], v[148:149] op_sel_hi:[1,0]
	s_waitcnt vmcnt(0)
	v_lshlrev_b32_e32 v172, 16, v154
	v_and_b32_e32 v173, 0xffff0000, v154
	v_lshlrev_b32_e32 v154, 16, v155
	v_and_b32_e32 v155, 0xffff0000, v155
	v_pk_fma_f32 v[128:129], v[128:129], v[188:189], v[154:155]
	v_lshlrev_b32_e32 v154, 16, v156
	v_and_b32_e32 v155, 0xffff0000, v156
	v_pk_fma_f32 v[122:123], v[122:123], v[182:183], v[154:155]
	v_lshlrev_b32_e32 v154, 16, v157
	v_and_b32_e32 v155, 0xffff0000, v157
	v_pk_fma_f32 v[126:127], v[126:127], v[186:187], v[172:173]
	v_pk_fma_f32 v[124:125], v[124:125], v[184:185], v[154:155]
	s_cbranch_vccz .LBB0_134
	v_cvt_pk_bf16_f32 v154, v126, v127
	v_cvt_pk_bf16_f32 v155, v128, v129
	v_cvt_pk_bf16_f32 v156, v122, v123
	v_cvt_pk_bf16_f32 v157, v124, v125
	global_store_dwordx4 v[136:137], v[154:157], off
	s_mov_b64 s[26:27], 0

; DI unsigned pk2(float lo, float hi) { f32x2_t v = {lo, hi}; bf16x2_t b = __builtin_convertvector(v, bf16x2_t); return __builtin_bit_cast(unsigned, b); }
; DI float bflo(unsigned u) { return __uint_as_float(u << 16); }
; DI float bfhi(unsigned u) { return __uint_as_float(u & 0xffff0000u); }
;     DI void operator()(pg8::f32x4 (&acc)[2][2][4][2], const pg8::Unit& u, int wr, int wc, int fr, int fq) const {
;     ...
;                 for (int bj = 0; bj < 2; ++bj) {
;                     const v4u xw = *(const v4u*)(XB + ro + bj * 128);
;                     const v4f g0 = *(const v4f*)(gpost + colb + bj * 128), g1 = *(const v4f*)(gpost + colb + bj * 128 + 4);
;                     const pg8::f32x4 a0 = acc[ai][bj][m][0], a1 = acc[ai][bj][m][1];
;                     float v[8];
;                     v[0] = bflo(xw.x) + a0[0] * r1 * g0[0]; v[1] = bfhi(xw.x) + a0[1] * r1 * g0[1]; v[2] = bflo(xw.y) + a0[2] * r1 * g0[2]; v[3] = bfhi(xw.y) + a0[3] * r1 * g0[3];
;                     v[4] = bflo(xw.z) + a1[0] * r1 * g1[0]; v[5] = bfhi(xw.z) + a1[1] * r1 * g1[1]; v[6] = bflo(xw.w) + a1[2] * r1 * g1[2]; v[7] = bfhi(xw.w) + a1[3] * r1 * g1[3];
;                     q += ((v[0] * v[0] + v[1] * v[1]) + (v[2] * v[2] + v[3] * v[3])) + ((v[4] * v[4] + v[5] * v[5]) + (v[6] * v[6] + v[7] * v[7]));
;                     if (last) { *(v4f*)(OUT + ro + bj * 128) = (v4f){v[0], v[1], v[2], v[3]}; *(v4f*)(OUT + ro + bj * 128 + 4) = (v4f){v[4], v[5], v[6], v[7]}; }
;                     else { v4u w; w.x = pk2(v[0], v[1]); w.y = pk2(v[2], v[3]); w.z = pk2(v[4], v[5]); w.w = pk2(v[6], v[7]); *(v4u*)(XB + ro + bj * 128) = w; }
.LBB0_136:
	global_load_dwordx4 v[182:185], v[130:131], off offset:512
	global_load_dwordx4 v[186:189], v[130:131], off offset:528
	v_mov_b32_e32 v149, v148
	v_cndmask_b32_e64 v153, 0, 1, s[18:19]
	v_pk_mul_f32 v[118:119], v[118:119], v[148:149]
	v_pk_mul_f32 v[120:121], v[120:121], v[148:149]
	v_pk_mul_f32 v[114:115], v[114:115], v[148:149]
	v_pk_mul_f32 v[116:117], v[116:117], v[148:149]
	v_cmp_ne_u32_e64 s[44:45], 1, v153
	s_andn2_b64 vcc, exec, s[18:19]
	s_mov_b64 s[26:27], -1
	s_waitcnt vmcnt(2)
	v_lshlrev_b32_e32 v148, 16, v206
	v_and_b32_e32 v149, 0xffff0000, v206
	v_lshlrev_b32_e32 v154, 16, v207
	v_and_b32_e32 v155, 0xffff0000, v207
	v_lshlrev_b32_e32 v172, 16, v208
	v_and_b32_e32 v173, 0xffff0000, v208
	v_lshlrev_b32_e32 v156, 16, v209
	v_and_b32_e32 v157, 0xffff0000, v209
	s_waitcnt vmcnt(1)
	v_pk_fma_f32 v[118:119], v[118:119], v[182:183], v[148:149]
	v_pk_fma_f32 v[120:121], v[120:121], v[184:185], v[154:155]
	s_waitcnt vmcnt(0)
	v_pk_fma_f32 v[114:115], v[114:115], v[186:187], v[172:173]
	v_pk_fma_f32 v[116:117], v[116:117], v[188:189], v[156:157]
	s_cbranch_vccnz .LBB0_138
	v_cvt_pk_bf16_f32 v154, v118, v119
	v_cvt_pk_bf16_f32 v155, v120, v121
	v_cvt_pk_bf16_f32 v156, v114, v115
	v_cvt_pk_bf16_f32 v157, v116, v117
	s_mov_b64 s[26:27], 0
	global_store_dwordx4 v[136:137], v[154:157], off offset:256

; DI unsigned pk2(float lo, float hi) { f32x2_t v = {lo, hi}; bf16x2_t b = __builtin_convertvector(v, bf16x2_t); return __builtin_bit_cast(unsigned, b); }
; DI float bflo(unsigned u) { return __uint_as_float(u << 16); }
; DI float bfhi(unsigned u) { return __uint_as_float(u & 0xffff0000u); }
;     DI void operator()(pg8::f32x4 (&acc)[2][2][4][2], const pg8::Unit& u, int wr, int wc, int fr, int fq) const {
;     ...
;         const int colb = u.pn * 256 + wc * 32 + 8 * fq;
; #pragma unroll
;         for (int ai = 0; ai < 2; ++ai)
; #pragma unroll
;             for (int m = 0; m < 4; ++m) {
;                 const int rl = ai * 128 + wr * 64 + m * 16 + fr; const float r1 = S[rl];
;                 const size_t ro = (size_t)(u.pm * 256 + rl) * 1024 + colb;
;                 float q = 0.f;
; #pragma unroll
;                 for (int bj = 0; bj < 2; ++bj) {
;                     const v4u xw = *(const v4u*)(XB + ro + bj * 128);
;                     const v4f g0 = *(const v4f*)(gpost + colb + bj * 128), g1 = *(const v4f*)(gpost + colb + bj * 128 + 4);
;                     const pg8::f32x4 a0 = acc[ai][bj][m][0], a1 = acc[ai][bj][m][1];
;                     float v[8];
;                     v[0] = bflo(xw.x) + a0[0] * r1 * g0[0]; v[1] = bfhi(xw.x) + a0[1] * r1 * g0[1]; v[2] = bflo(xw.y) + a0[2] * r1 * g0[2]; v[3] = bfhi(xw.y) + a0[3] * r1 * g0[3];
;                     v[4] = bflo(xw.z) + a1[0] * r1 * g1[0]; v[5] = bfhi(xw.z) + a1[1] * r1 * g1[1]; v[6] = bflo(xw.w) + a1[2] * r1 * g1[2]; v[7] = bfhi(xw.w) + a1[3] * r1 * g1[3];
;                     q += ((v[0] * v[0] + v[1] * v[1]) + (v[2] * v[2] + v[3] * v[3])) + ((v[4] * v[4] + v[5] * v[5]) + (v[6] * v[6] + v[7] * v[7]));
;                     if (last) { *(v4f*)(OUT + ro + bj * 128) = (v4f){v[0], v[1], v[2], v[3]}; *(v4f*)(OUT + ro + bj * 128 + 4) = (v4f){v[4], v[5], v[6], v[7]}; }
;                     else { v4u w; w.x = pk2(v[0], v[1]); w.y = pk2(v[2], v[3]); w.z = pk2(v[4], v[5]); w.w = pk2(v[6], v[7]); *(v4u*)(XB + ro + bj * 128) = w; }
.LBB0_142:
	s_or_b64 exec, exec, s[24:25]
	v_lshl_add_u32 v114, v162, 2, s68
	global_load_dwordx4 v[122:125], v[130:131], off offset:16
	global_load_dwordx4 v[126:129], v[130:131], off
	ds_read_b32 v118, v114
	v_add_u32_e32 v114, v152, v162
	s_waitcnt lgkmcnt(1)
	v_ashrrev_i32_e32 v115, 31, v114
	v_lshlrev_b64 v[116:117], 10, v[114:115]
	v_lshl_add_u64 v[120:121], v[116:117], 0, v[132:133]
	v_lshl_add_u64 v[116:117], v[120:121], 1, s[22:23]
	global_load_dwordx4 v[134:137], v[116:117], off
	global_load_dwordx4 v[206:209], v[116:117], off offset:256
	s_waitcnt lgkmcnt(0)
	v_pk_mul_f32 v[110:111], v[110:111], v[118:119] op_sel_hi:[1,0]
	v_pk_mul_f32 v[112:113], v[112:113], v[118:119] op_sel_hi:[1,0]
	v_pk_mul_f32 v[106:107], v[106:107], v[118:119] op_sel_hi:[1,0]
	v_pk_mul_f32 v[108:109], v[108:109], v[118:119] op_sel_hi:[1,0]
	s_mov_b64 s[24:25], -1
	s_and_b64 vcc, exec, s[44:45]
	s_waitcnt vmcnt(0)
	v_lshlrev_b32_e32 v148, 16, v134
	v_and_b32_e32 v149, 0xffff0000, v134
	v_pk_fma_f32 v[110:111], v[126:127], v[110:111], v[148:149]
	v_lshlrev_b32_e32 v126, 16, v135
	v_and_b32_e32 v127, 0xffff0000, v135
	v_pk_fma_f32 v[112:113], v[128:129], v[112:113], v[126:127]
	v_lshlrev_b32_e32 v126, 16, v136
	v_and_b32_e32 v127, 0xffff0000, v136
	v_pk_fma_f32 v[106:107], v[122:123], v[106:107], v[126:127]
	v_lshlrev_b32_e32 v122, 16, v137
	v_and_b32_e32 v123, 0xffff0000, v137
	v_pk_fma_f32 v[108:109], v[124:125], v[108:109], v[122:123]
	s_cbranch_vccnz .LBB0_144
	v_cvt_pk_bf16_f32 v122, v110, v111
	v_cvt_pk_bf16_f32 v123, v112, v113
	v_cvt_pk_bf16_f32 v124, v106, v107
	v_cvt_pk_bf16_f32 v125, v108, v109
	s_mov_b64 s[24:25], 0
	global_store_dwordx4 v[116:117], v[122:125], off

; DI unsigned pk2(float lo, float hi) { f32x2_t v = {lo, hi}; bf16x2_t b = __builtin_convertvector(v, bf16x2_t); return __builtin_bit_cast(unsigned, b); }
; DI float bflo(unsigned u) { return __uint_as_float(u << 16); }
; DI float bfhi(unsigned u) { return __uint_as_float(u & 0xffff0000u); }
;     DI void operator()(pg8::f32x4 (&acc)[2][2][4][2], const pg8::Unit& u, int wr, int wc, int fr, int fq) const {
;     ...
;                 for (int bj = 0; bj < 2; ++bj) {
;                     const v4u xw = *(const v4u*)(XB + ro + bj * 128);
;                     const v4f g0 = *(const v4f*)(gpost + colb + bj * 128), g1 = *(const v4f*)(gpost + colb + bj * 128 + 4);
;                     const pg8::f32x4 a0 = acc[ai][bj][m][0], a1 = acc[ai][bj][m][1];
;                     float v[8];
;                     v[0] = bflo(xw.x) + a0[0] * r1 * g0[0]; v[1] = bfhi(xw.x) + a0[1] * r1 * g0[1]; v[2] = bflo(xw.y) + a0[2] * r1 * g0[2]; v[3] = bfhi(xw.y) + a0[3] * r1 * g0[3];
;                     v[4] = bflo(xw.z) + a1[0] * r1 * g1[0]; v[5] = bfhi(xw.z) + a1[1] * r1 * g1[1]; v[6] = bflo(xw.w) + a1[2] * r1 * g1[2]; v[7] = bfhi(xw.w) + a1[3] * r1 * g1[3];
;                     q += ((v[0] * v[0] + v[1] * v[1]) + (v[2] * v[2] + v[3] * v[3])) + ((v[4] * v[4] + v[5] * v[5]) + (v[6] * v[6] + v[7] * v[7]));
;                     if (last) { *(v4f*)(OUT + ro + bj * 128) = (v4f){v[0], v[1], v[2], v[3]}; *(v4f*)(OUT + ro + bj * 128 + 4) = (v4f){v[4], v[5], v[6], v[7]}; }
;                     else { v4u w; w.x = pk2(v[0], v[1]); w.y = pk2(v[2], v[3]); w.z = pk2(v[4], v[5]); w.w = pk2(v[6], v[7]); *(v4u*)(XB + ro + bj * 128) = w; }
.LBB0_146:
	global_load_dwordx4 v[126:129], v[130:131], off offset:512
	global_load_dwordx4 v[134:137], v[130:131], off offset:528
	v_mov_b32_e32 v119, v118
	v_pk_mul_f32 v[102:103], v[102:103], v[118:119]
	v_pk_mul_f32 v[104:105], v[104:105], v[118:119]
	v_pk_mul_f32 v[98:99], v[98:99], v[118:119]
	v_pk_mul_f32 v[100:101], v[100:101], v[118:119]
	s_and_b64 vcc, exec, s[44:45]
	s_mov_b64 s[24:25], -1
	s_waitcnt vmcnt(2)
	v_lshlrev_b32_e32 v118, 16, v206
	v_and_b32_e32 v119, 0xffff0000, v206
	v_lshlrev_b32_e32 v122, 16, v207
	v_and_b32_e32 v123, 0xffff0000, v207
	v_lshlrev_b32_e32 v148, 16, v208
	v_and_b32_e32 v149, 0xffff0000, v208
	v_lshlrev_b32_e32 v124, 16, v209
	v_and_b32_e32 v125, 0xffff0000, v209
	s_waitcnt vmcnt(1)
	v_pk_fma_f32 v[102:103], v[102:103], v[126:127], v[118:119]
	v_pk_fma_f32 v[104:105], v[104:105], v[128:129], v[122:123]
	s_waitcnt vmcnt(0)
	v_pk_fma_f32 v[98:99], v[98:99], v[134:135], v[148:149]
	v_pk_fma_f32 v[100:101], v[100:101], v[136:137], v[124:125]
	s_cbranch_vccnz .LBB0_148
	v_cvt_pk_bf16_f32 v122, v102, v103
	v_cvt_pk_bf16_f32 v123, v104, v105
	v_cvt_pk_bf16_f32 v124, v98, v99
	v_cvt_pk_bf16_f32 v125, v100, v101
	s_mov_b64 s[24:25], 0
	global_store_dwordx4 v[116:117], v[122:125], off offset:256

; DI unsigned pk2(float lo, float hi) { f32x2_t v = {lo, hi}; bf16x2_t b = __builtin_convertvector(v, bf16x2_t); return __builtin_bit_cast(unsigned, b); }
; DI float bflo(unsigned u) { return __uint_as_float(u << 16); }
; DI float bfhi(unsigned u) { return __uint_as_float(u & 0xffff0000u); }
;     DI void operator()(pg8::f32x4 (&acc)[2][2][4][2], const pg8::Unit& u, int wr, int wc, int fr, int fq) const {
;     ...
;         const int colb = u.pn * 256 + wc * 32 + 8 * fq;
; #pragma unroll
;         for (int ai = 0; ai < 2; ++ai)
; #pragma unroll
;             for (int m = 0; m < 4; ++m) {
;                 const int rl = ai * 128 + wr * 64 + m * 16 + fr; const float r1 = S[rl];
;                 const size_t ro = (size_t)(u.pm * 256 + rl) * 1024 + colb;
;                 float q = 0.f;
; #pragma unroll
;                 for (int bj = 0; bj < 2; ++bj) {
;                     const v4u xw = *(const v4u*)(XB + ro + bj * 128);
;                     const v4f g0 = *(const v4f*)(gpost + colb + bj * 128), g1 = *(const v4f*)(gpost + colb + bj * 128 + 4);
;                     const pg8::f32x4 a0 = acc[ai][bj][m][0], a1 = acc[ai][bj][m][1];
;                     float v[8];
;                     v[0] = bflo(xw.x) + a0[0] * r1 * g0[0]; v[1] = bfhi(xw.x) + a0[1] * r1 * g0[1]; v[2] = bflo(xw.y) + a0[2] * r1 * g0[2]; v[3] = bfhi(xw.y) + a0[3] * r1 * g0[3];
;                     v[4] = bflo(xw.z) + a1[0] * r1 * g1[0]; v[5] = bfhi(xw.z) + a1[1] * r1 * g1[1]; v[6] = bflo(xw.w) + a1[2] * r1 * g1[2]; v[7] = bfhi(xw.w) + a1[3] * r1 * g1[3];
;                     q += ((v[0] * v[0] + v[1] * v[1]) + (v[2] * v[2] + v[3] * v[3])) + ((v[4] * v[4] + v[5] * v[5]) + (v[6] * v[6] + v[7] * v[7]));
;                     if (last) { *(v4f*)(OUT + ro + bj * 128) = (v4f){v[0], v[1], v[2], v[3]}; *(v4f*)(OUT + ro + bj * 128 + 4) = (v4f){v[4], v[5], v[6], v[7]}; }
;                     else { v4u w; w.x = pk2(v[0], v[1]); w.y = pk2(v[2], v[3]); w.z = pk2(v[4], v[5]); w.w = pk2(v[6], v[7]); *(v4u*)(XB + ro + bj * 128) = w; }
.LBB0_152:
	s_or_b64 exec, exec, s[24:25]
	v_lshl_add_u32 v98, v163, 2, s68
	ds_read_b32 v102, v98
	v_add_u32_e32 v98, v152, v163
	s_waitcnt lgkmcnt(1)
	v_ashrrev_i32_e32 v99, 31, v98
	v_lshlrev_b64 v[100:101], 10, v[98:99]
	v_lshl_add_u64 v[104:105], v[100:101], 0, v[132:133]
	v_lshl_add_u64 v[100:101], v[104:105], 1, s[22:23]
	global_load_dwordx4 v[106:109], v[100:101], off
	global_load_dwordx4 v[206:209], v[100:101], off offset:256
	global_load_dwordx4 v[110:113], v[130:131], off offset:16
	global_load_dwordx4 v[114:117], v[130:131], off
	s_waitcnt lgkmcnt(0)
	v_pk_mul_f32 v[96:97], v[96:97], v[102:103] op_sel_hi:[1,0]
	v_pk_mul_f32 v[90:91], v[90:91], v[102:103] op_sel_hi:[1,0]
	v_pk_mul_f32 v[94:95], v[94:95], v[102:103] op_sel_hi:[1,0]
	v_pk_mul_f32 v[92:93], v[92:93], v[102:103] op_sel_hi:[1,0]
	s_mov_b64 s[24:25], -1
	s_and_b64 vcc, exec, s[44:45]
	s_waitcnt vmcnt(2)
	v_lshlrev_b32_e32 v118, 16, v106
	v_and_b32_e32 v119, 0xffff0000, v106
	v_lshlrev_b32_e32 v106, 16, v107
	v_and_b32_e32 v107, 0xffff0000, v107
	s_waitcnt vmcnt(0)
	v_pk_fma_f32 v[96:97], v[96:97], v[116:117], v[106:107]
	v_lshlrev_b32_e32 v106, 16, v108
	v_and_b32_e32 v107, 0xffff0000, v108
	v_pk_fma_f32 v[90:91], v[90:91], v[110:111], v[106:107]
	v_lshlrev_b32_e32 v106, 16, v109
	v_and_b32_e32 v107, 0xffff0000, v109
	v_pk_fma_f32 v[94:95], v[94:95], v[114:115], v[118:119]
	v_pk_fma_f32 v[92:93], v[92:93], v[112:113], v[106:107]
	s_cbranch_vccnz .LBB0_154
	v_cvt_pk_bf16_f32 v106, v94, v95
	v_cvt_pk_bf16_f32 v107, v96, v97
	v_cvt_pk_bf16_f32 v108, v90, v91
	v_cvt_pk_bf16_f32 v109, v92, v93
	s_mov_b64 s[24:25], 0
	global_store_dwordx4 v[100:101], v[106:109], off

; DI unsigned pk2(float lo, float hi) { f32x2_t v = {lo, hi}; bf16x2_t b = __builtin_convertvector(v, bf16x2_t); return __builtin_bit_cast(unsigned, b); }
; DI float bflo(unsigned u) { return __uint_as_float(u << 16); }
; DI float bfhi(unsigned u) { return __uint_as_float(u & 0xffff0000u); }
;     DI void operator()(pg8::f32x4 (&acc)[2][2][4][2], const pg8::Unit& u, int wr, int wc, int fr, int fq) const {
;     ...
;                 for (int bj = 0; bj < 2; ++bj) {
;                     const v4u xw = *(const v4u*)(XB + ro + bj * 128);
;                     const v4f g0 = *(const v4f*)(gpost + colb + bj * 128), g1 = *(const v4f*)(gpost + colb + bj * 128 + 4);
;                     const pg8::f32x4 a0 = acc[ai][bj][m][0], a1 = acc[ai][bj][m][1];
;                     float v[8];
;                     v[0] = bflo(xw.x) + a0[0] * r1 * g0[0]; v[1] = bfhi(xw.x) + a0[1] * r1 * g0[1]; v[2] = bflo(xw.y) + a0[2] * r1 * g0[2]; v[3] = bfhi(xw.y) + a0[3] * r1 * g0[3];
;                     v[4] = bflo(xw.z) + a1[0] * r1 * g1[0]; v[5] = bfhi(xw.z) + a1[1] * r1 * g1[1]; v[6] = bflo(xw.w) + a1[2] * r1 * g1[2]; v[7] = bfhi(xw.w) + a1[3] * r1 * g1[3];
;                     q += ((v[0] * v[0] + v[1] * v[1]) + (v[2] * v[2] + v[3] * v[3])) + ((v[4] * v[4] + v[5] * v[5]) + (v[6] * v[6] + v[7] * v[7]));
;                     if (last) { *(v4f*)(OUT + ro + bj * 128) = (v4f){v[0], v[1], v[2], v[3]}; *(v4f*)(OUT + ro + bj * 128 + 4) = (v4f){v[4], v[5], v[6], v[7]}; }
;                     else { v4u w; w.x = pk2(v[0], v[1]); w.y = pk2(v[2], v[3]); w.z = pk2(v[4], v[5]); w.w = pk2(v[6], v[7]); *(v4u*)(XB + ro + bj * 128) = w; }
.LBB0_156:
	global_load_dwordx4 v[110:113], v[130:131], off offset:512
	global_load_dwordx4 v[114:117], v[130:131], off offset:528
	v_mov_b32_e32 v103, v102
	v_pk_mul_f32 v[86:87], v[86:87], v[102:103]
	v_pk_mul_f32 v[88:89], v[88:89], v[102:103]
	v_pk_mul_f32 v[82:83], v[82:83], v[102:103]
	v_pk_mul_f32 v[84:85], v[84:85], v[102:103]
	s_and_b64 vcc, exec, s[44:45]
	s_mov_b64 s[24:25], -1
	s_waitcnt vmcnt(2)
	v_lshlrev_b32_e32 v102, 16, v206
	v_and_b32_e32 v103, 0xffff0000, v206
	v_lshlrev_b32_e32 v106, 16, v207
	v_and_b32_e32 v107, 0xffff0000, v207
	v_lshlrev_b32_e32 v118, 16, v208
	v_and_b32_e32 v119, 0xffff0000, v208
	v_lshlrev_b32_e32 v108, 16, v209
	v_and_b32_e32 v109, 0xffff0000, v209
	s_waitcnt vmcnt(1)
	v_pk_fma_f32 v[86:87], v[86:87], v[110:111], v[102:103]
	v_pk_fma_f32 v[88:89], v[88:89], v[112:113], v[106:107]
	s_waitcnt vmcnt(0)
	v_pk_fma_f32 v[82:83], v[82:83], v[114:115], v[118:119]
	v_pk_fma_f32 v[84:85], v[84:85], v[116:117], v[108:109]
	s_cbranch_vccnz .LBB0_158
	v_cvt_pk_bf16_f32 v106, v86, v87
	v_cvt_pk_bf16_f32 v107, v88, v89
	v_cvt_pk_bf16_f32 v108, v82, v83
	v_cvt_pk_bf16_f32 v109, v84, v85
	s_mov_b64 s[24:25], 0
	global_store_dwordx4 v[100:101], v[106:109], off offset:256

; DI unsigned pk2(float lo, float hi) { f32x2_t v = {lo, hi}; bf16x2_t b = __builtin_convertvector(v, bf16x2_t); return __builtin_bit_cast(unsigned, b); }
; DI float bflo(unsigned u) { return __uint_as_float(u << 16); }
; DI float bfhi(unsigned u) { return __uint_as_float(u & 0xffff0000u); }
;     DI void operator()(pg8::f32x4 (&acc)[2][2][4][2], const pg8::Unit& u, int wr, int wc, int fr, int fq) const {
;     ...
;         const int colb = u.pn * 256 + wc * 32 + 8 * fq;
; #pragma unroll
;         for (int ai = 0; ai < 2; ++ai)
; #pragma unroll
;             for (int m = 0; m < 4; ++m) {
;                 const int rl = ai * 128 + wr * 64 + m * 16 + fr; const float r1 = S[rl];
;                 const size_t ro = (size_t)(u.pm * 256 + rl) * 1024 + colb;
;                 float q = 0.f;
; #pragma unroll
;                 for (int bj = 0; bj < 2; ++bj) {
;                     const v4u xw = *(const v4u*)(XB + ro + bj * 128);
;                     const v4f g0 = *(const v4f*)(gpost + colb + bj * 128), g1 = *(const v4f*)(gpost + colb + bj * 128 + 4);
;                     const pg8::f32x4 a0 = acc[ai][bj][m][0], a1 = acc[ai][bj][m][1];
;                     float v[8];
;                     v[0] = bflo(xw.x) + a0[0] * r1 * g0[0]; v[1] = bfhi(xw.x) + a0[1] * r1 * g0[1]; v[2] = bflo(xw.y) + a0[2] * r1 * g0[2]; v[3] = bfhi(xw.y) + a0[3] * r1 * g0[3];
;                     v[4] = bflo(xw.z) + a1[0] * r1 * g1[0]; v[5] = bfhi(xw.z) + a1[1] * r1 * g1[1]; v[6] = bflo(xw.w) + a1[2] * r1 * g1[2]; v[7] = bfhi(xw.w) + a1[3] * r1 * g1[3];
;                     q += ((v[0] * v[0] + v[1] * v[1]) + (v[2] * v[2] + v[3] * v[3])) + ((v[4] * v[4] + v[5] * v[5]) + (v[6] * v[6] + v[7] * v[7]));
;                     if (last) { *(v4f*)(OUT + ro + bj * 128) = (v4f){v[0], v[1], v[2], v[3]}; *(v4f*)(OUT + ro + bj * 128 + 4) = (v4f){v[4], v[5], v[6], v[7]}; }
;                     else { v4u w; w.x = pk2(v[0], v[1]); w.y = pk2(v[2], v[3]); w.z = pk2(v[4], v[5]); w.w = pk2(v[6], v[7]); *(v4u*)(XB + ro + bj * 128) = w; }
.LBB0_162:
	s_or_b64 exec, exec, s[24:25]
	v_add_u32_e32 v82, v152, v164
	s_waitcnt lgkmcnt(0)
	v_ashrrev_i32_e32 v83, 31, v82
	v_lshlrev_b64 v[84:85], 10, v[82:83]
	v_lshl_add_u64 v[88:89], v[84:85], 0, v[132:133]
	v_lshl_add_u64 v[84:85], v[88:89], 1, s[22:23]
	global_load_dwordx4 v[90:93], v[130:131], off offset:16
	global_load_dwordx4 v[94:97], v[130:131], off
	global_load_dwordx4 v[98:101], v[84:85], off
	global_load_dwordx4 v[206:209], v[84:85], off offset:256
	ds_read_b32 v86, v170
	s_mov_b64 s[24:25], -1
	s_and_b64 vcc, exec, s[44:45]
	s_waitcnt lgkmcnt(0)
	v_pk_mul_f32 v[78:79], v[78:79], v[86:87] op_sel_hi:[1,0]
	v_pk_mul_f32 v[80:81], v[80:81], v[86:87] op_sel_hi:[1,0]
	v_pk_mul_f32 v[74:75], v[74:75], v[86:87] op_sel_hi:[1,0]
	v_pk_mul_f32 v[76:77], v[76:77], v[86:87] op_sel_hi:[1,0]
	s_waitcnt vmcnt(0)
	v_lshlrev_b32_e32 v102, 16, v98
	v_and_b32_e32 v103, 0xffff0000, v98
	v_pk_fma_f32 v[78:79], v[94:95], v[78:79], v[102:103]
	v_lshlrev_b32_e32 v94, 16, v99
	v_and_b32_e32 v95, 0xffff0000, v99
	v_pk_fma_f32 v[80:81], v[96:97], v[80:81], v[94:95]
	v_lshlrev_b32_e32 v94, 16, v100
	v_and_b32_e32 v95, 0xffff0000, v100
	v_pk_fma_f32 v[74:75], v[90:91], v[74:75], v[94:95]
	v_lshlrev_b32_e32 v90, 16, v101
	v_and_b32_e32 v91, 0xffff0000, v101
	v_pk_fma_f32 v[76:77], v[92:93], v[76:77], v[90:91]
	s_cbranch_vccnz .LBB0_164
	v_cvt_pk_bf16_f32 v90, v78, v79
	v_cvt_pk_bf16_f32 v91, v80, v81
	v_cvt_pk_bf16_f32 v92, v74, v75
	v_cvt_pk_bf16_f32 v93, v76, v77
	s_mov_b64 s[24:25], 0
	global_store_dwordx4 v[84:85], v[90:93], off

; DI unsigned pk2(float lo, float hi) { f32x2_t v = {lo, hi}; bf16x2_t b = __builtin_convertvector(v, bf16x2_t); return __builtin_bit_cast(unsigned, b); }
; DI float bflo(unsigned u) { return __uint_as_float(u << 16); }
; DI float bfhi(unsigned u) { return __uint_as_float(u & 0xffff0000u); }
;     DI void operator()(pg8::f32x4 (&acc)[2][2][4][2], const pg8::Unit& u, int wr, int wc, int fr, int fq) const {
;     ...
;                 for (int bj = 0; bj < 2; ++bj) {
;                     const v4u xw = *(const v4u*)(XB + ro + bj * 128);
;                     const v4f g0 = *(const v4f*)(gpost + colb + bj * 128), g1 = *(const v4f*)(gpost + colb + bj * 128 + 4);
;                     const pg8::f32x4 a0 = acc[ai][bj][m][0], a1 = acc[ai][bj][m][1];
;                     float v[8];
;                     v[0] = bflo(xw.x) + a0[0] * r1 * g0[0]; v[1] = bfhi(xw.x) + a0[1] * r1 * g0[1]; v[2] = bflo(xw.y) + a0[2] * r1 * g0[2]; v[3] = bfhi(xw.y) + a0[3] * r1 * g0[3];
;                     v[4] = bflo(xw.z) + a1[0] * r1 * g1[0]; v[5] = bfhi(xw.z) + a1[1] * r1 * g1[1]; v[6] = bflo(xw.w) + a1[2] * r1 * g1[2]; v[7] = bfhi(xw.w) + a1[3] * r1 * g1[3];
;                     q += ((v[0] * v[0] + v[1] * v[1]) + (v[2] * v[2] + v[3] * v[3])) + ((v[4] * v[4] + v[5] * v[5]) + (v[6] * v[6] + v[7] * v[7]));
;                     if (last) { *(v4f*)(OUT + ro + bj * 128) = (v4f){v[0], v[1], v[2], v[3]}; *(v4f*)(OUT + ro + bj * 128 + 4) = (v4f){v[4], v[5], v[6], v[7]}; }
;                     else { v4u w; w.x = pk2(v[0], v[1]); w.y = pk2(v[2], v[3]); w.z = pk2(v[4], v[5]); w.w = pk2(v[6], v[7]); *(v4u*)(XB + ro + bj * 128) = w; }
.LBB0_166:
	global_load_dwordx4 v[94:97], v[130:131], off offset:512
	global_load_dwordx4 v[98:101], v[130:131], off offset:528
	v_mov_b32_e32 v87, v86
	v_pk_mul_f32 v[70:71], v[70:71], v[86:87]
	v_pk_mul_f32 v[72:73], v[72:73], v[86:87]
	v_pk_mul_f32 v[66:67], v[66:67], v[86:87]
	v_pk_mul_f32 v[68:69], v[68:69], v[86:87]
	s_and_b64 vcc, exec, s[44:45]
	s_mov_b64 s[24:25], -1
	s_waitcnt vmcnt(2)
	v_lshlrev_b32_e32 v86, 16, v206
	v_and_b32_e32 v87, 0xffff0000, v206
	v_lshlrev_b32_e32 v90, 16, v207
	v_and_b32_e32 v91, 0xffff0000, v207
	v_lshlrev_b32_e32 v102, 16, v208
	v_and_b32_e32 v103, 0xffff0000, v208
	v_lshlrev_b32_e32 v92, 16, v209
	v_and_b32_e32 v93, 0xffff0000, v209
	s_waitcnt vmcnt(1)
	v_pk_fma_f32 v[70:71], v[70:71], v[94:95], v[86:87]
	v_pk_fma_f32 v[72:73], v[72:73], v[96:97], v[90:91]
	s_waitcnt vmcnt(0)
	v_pk_fma_f32 v[66:67], v[66:67], v[98:99], v[102:103]
	v_pk_fma_f32 v[68:69], v[68:69], v[100:101], v[92:93]
	s_cbranch_vccnz .LBB0_168
	v_cvt_pk_bf16_f32 v90, v70, v71
	v_cvt_pk_bf16_f32 v91, v72, v73
	v_cvt_pk_bf16_f32 v92, v66, v67
	v_cvt_pk_bf16_f32 v93, v68, v69
	s_mov_b64 s[24:25], 0
	global_store_dwordx4 v[84:85], v[90:93], off offset:256

; DI unsigned pk2(float lo, float hi) { f32x2_t v = {lo, hi}; bf16x2_t b = __builtin_convertvector(v, bf16x2_t); return __builtin_bit_cast(unsigned, b); }
; DI float bflo(unsigned u) { return __uint_as_float(u << 16); }
; DI float bfhi(unsigned u) { return __uint_as_float(u & 0xffff0000u); }
;     DI void operator()(pg8::f32x4 (&acc)[2][2][4][2], const pg8::Unit& u, int wr, int wc, int fr, int fq) const {
;     ...
;         const int colb = u.pn * 256 + wc * 32 + 8 * fq;
; #pragma unroll
;         for (int ai = 0; ai < 2; ++ai)
; #pragma unroll
;             for (int m = 0; m < 4; ++m) {
;                 const int rl = ai * 128 + wr * 64 + m * 16 + fr; const float r1 = S[rl];
;                 const size_t ro = (size_t)(u.pm * 256 + rl) * 1024 + colb;
;                 float q = 0.f;
; #pragma unroll
;                 for (int bj = 0; bj < 2; ++bj) {
;                     const v4u xw = *(const v4u*)(XB + ro + bj * 128);
;                     const v4f g0 = *(const v4f*)(gpost + colb + bj * 128), g1 = *(const v4f*)(gpost + colb + bj * 128 + 4);
;                     const pg8::f32x4 a0 = acc[ai][bj][m][0], a1 = acc[ai][bj][m][1];
;                     float v[8];
;                     v[0] = bflo(xw.x) + a0[0] * r1 * g0[0]; v[1] = bfhi(xw.x) + a0[1] * r1 * g0[1]; v[2] = bflo(xw.y) + a0[2] * r1 * g0[2]; v[3] = bfhi(xw.y) + a0[3] * r1 * g0[3];
;                     v[4] = bflo(xw.z) + a1[0] * r1 * g1[0]; v[5] = bfhi(xw.z) + a1[1] * r1 * g1[1]; v[6] = bflo(xw.w) + a1[2] * r1 * g1[2]; v[7] = bfhi(xw.w) + a1[3] * r1 * g1[3];
;                     q += ((v[0] * v[0] + v[1] * v[1]) + (v[2] * v[2] + v[3] * v[3])) + ((v[4] * v[4] + v[5] * v[5]) + (v[6] * v[6] + v[7] * v[7]));
;                     if (last) { *(v4f*)(OUT + ro + bj * 128) = (v4f){v[0], v[1], v[2], v[3]}; *(v4f*)(OUT + ro + bj * 128 + 4) = (v4f){v[4], v[5], v[6], v[7]}; }
;                     else { v4u w; w.x = pk2(v[0], v[1]); w.y = pk2(v[2], v[3]); w.z = pk2(v[4], v[5]); w.w = pk2(v[6], v[7]); *(v4u*)(XB + ro + bj * 128) = w; }
.LBB0_172:
	s_or_b64 exec, exec, s[24:25]
	v_add_u32_e32 v66, v152, v165
	s_waitcnt lgkmcnt(0)
	v_ashrrev_i32_e32 v67, 31, v66
	v_lshlrev_b64 v[68:69], 10, v[66:67]
	v_lshl_add_u64 v[72:73], v[68:69], 0, v[132:133]
	v_lshl_add_u64 v[68:69], v[72:73], 1, s[22:23]
	ds_read_b32 v70, v171
	global_load_dwordx4 v[74:77], v[68:69], off
	global_load_dwordx4 v[206:209], v[68:69], off offset:256
	global_load_dwordx4 v[78:81], v[130:131], off offset:16
	global_load_dwordx4 v[82:85], v[130:131], off
	s_mov_b64 s[24:25], -1
	s_and_b64 vcc, exec, s[44:45]
	s_waitcnt lgkmcnt(0)
	v_pk_mul_f32 v[62:63], v[62:63], v[70:71] op_sel_hi:[1,0]
	v_pk_mul_f32 v[56:57], v[56:57], v[70:71] op_sel_hi:[1,0]
	v_pk_mul_f32 v[60:61], v[60:61], v[70:71] op_sel_hi:[1,0]
	v_pk_mul_f32 v[58:59], v[58:59], v[70:71] op_sel_hi:[1,0]
	s_waitcnt vmcnt(2)
	v_lshlrev_b32_e32 v86, 16, v74
	v_and_b32_e32 v87, 0xffff0000, v74
	v_lshlrev_b32_e32 v74, 16, v75
	v_and_b32_e32 v75, 0xffff0000, v75
	s_waitcnt vmcnt(0)
	v_pk_fma_f32 v[62:63], v[62:63], v[84:85], v[74:75]
	v_lshlrev_b32_e32 v74, 16, v76
	v_and_b32_e32 v75, 0xffff0000, v76
	v_pk_fma_f32 v[56:57], v[56:57], v[78:79], v[74:75]
	v_lshlrev_b32_e32 v74, 16, v77
	v_and_b32_e32 v75, 0xffff0000, v77
	v_pk_fma_f32 v[60:61], v[60:61], v[82:83], v[86:87]
	v_pk_fma_f32 v[58:59], v[58:59], v[80:81], v[74:75]
	s_cbranch_vccnz .LBB0_174
	v_cvt_pk_bf16_f32 v74, v60, v61
	v_cvt_pk_bf16_f32 v75, v62, v63
	v_cvt_pk_bf16_f32 v76, v56, v57
	v_cvt_pk_bf16_f32 v77, v58, v59
	s_mov_b64 s[24:25], 0
	global_store_dwordx4 v[68:69], v[74:77], off

; DI unsigned pk2(float lo, float hi) { f32x2_t v = {lo, hi}; bf16x2_t b = __builtin_convertvector(v, bf16x2_t); return __builtin_bit_cast(unsigned, b); }
; DI float bflo(unsigned u) { return __uint_as_float(u << 16); }
; DI float bfhi(unsigned u) { return __uint_as_float(u & 0xffff0000u); }
;     DI void operator()(pg8::f32x4 (&acc)[2][2][4][2], const pg8::Unit& u, int wr, int wc, int fr, int fq) const {
;     ...
;                 for (int bj = 0; bj < 2; ++bj) {
;                     const v4u xw = *(const v4u*)(XB + ro + bj * 128);
;                     const v4f g0 = *(const v4f*)(gpost + colb + bj * 128), g1 = *(const v4f*)(gpost + colb + bj * 128 + 4);
;                     const pg8::f32x4 a0 = acc[ai][bj][m][0], a1 = acc[ai][bj][m][1];
;                     float v[8];
;                     v[0] = bflo(xw.x) + a0[0] * r1 * g0[0]; v[1] = bfhi(xw.x) + a0[1] * r1 * g0[1]; v[2] = bflo(xw.y) + a0[2] * r1 * g0[2]; v[3] = bfhi(xw.y) + a0[3] * r1 * g0[3];
;                     v[4] = bflo(xw.z) + a1[0] * r1 * g1[0]; v[5] = bfhi(xw.z) + a1[1] * r1 * g1[1]; v[6] = bflo(xw.w) + a1[2] * r1 * g1[2]; v[7] = bfhi(xw.w) + a1[3] * r1 * g1[3];
;                     q += ((v[0] * v[0] + v[1] * v[1]) + (v[2] * v[2] + v[3] * v[3])) + ((v[4] * v[4] + v[5] * v[5]) + (v[6] * v[6] + v[7] * v[7]));
;                     if (last) { *(v4f*)(OUT + ro + bj * 128) = (v4f){v[0], v[1], v[2], v[3]}; *(v4f*)(OUT + ro + bj * 128 + 4) = (v4f){v[4], v[5], v[6], v[7]}; }
;                     else { v4u w; w.x = pk2(v[0], v[1]); w.y = pk2(v[2], v[3]); w.z = pk2(v[4], v[5]); w.w = pk2(v[6], v[7]); *(v4u*)(XB + ro + bj * 128) = w; }
.LBB0_176:
	global_load_dwordx4 v[78:81], v[130:131], off offset:512
	global_load_dwordx4 v[82:85], v[130:131], off offset:528
	v_mov_b32_e32 v71, v70
	v_pk_mul_f32 v[52:53], v[52:53], v[70:71]
	v_pk_mul_f32 v[54:55], v[54:55], v[70:71]
	v_pk_mul_f32 v[48:49], v[48:49], v[70:71]
	v_pk_mul_f32 v[50:51], v[50:51], v[70:71]
	s_and_b64 vcc, exec, s[44:45]
	s_mov_b64 s[24:25], -1
	s_waitcnt vmcnt(2)
	v_lshlrev_b32_e32 v70, 16, v206
	v_and_b32_e32 v71, 0xffff0000, v206
	v_lshlrev_b32_e32 v74, 16, v207
	v_and_b32_e32 v75, 0xffff0000, v207
	v_lshlrev_b32_e32 v86, 16, v208
	v_and_b32_e32 v87, 0xffff0000, v208
	v_lshlrev_b32_e32 v76, 16, v209
	v_and_b32_e32 v77, 0xffff0000, v209
	s_waitcnt vmcnt(1)
	v_pk_fma_f32 v[52:53], v[52:53], v[78:79], v[70:71]
	v_pk_fma_f32 v[54:55], v[54:55], v[80:81], v[74:75]
	s_waitcnt vmcnt(0)
	v_pk_fma_f32 v[48:49], v[48:49], v[82:83], v[86:87]
	v_pk_fma_f32 v[50:51], v[50:51], v[84:85], v[76:77]
	s_cbranch_vccnz .LBB0_178
	v_cvt_pk_bf16_f32 v74, v52, v53
	v_cvt_pk_bf16_f32 v75, v54, v55
	v_cvt_pk_bf16_f32 v76, v48, v49
	v_cvt_pk_bf16_f32 v77, v50, v51
	s_mov_b64 s[24:25], 0
	global_store_dwordx4 v[68:69], v[74:77], off offset:256

; DI unsigned pk2(float lo, float hi) { f32x2_t v = {lo, hi}; bf16x2_t b = __builtin_convertvector(v, bf16x2_t); return __builtin_bit_cast(unsigned, b); }
; DI float bflo(unsigned u) { return __uint_as_float(u << 16); }
; DI float bfhi(unsigned u) { return __uint_as_float(u & 0xffff0000u); }
;     DI void operator()(pg8::f32x4 (&acc)[2][2][4][2], const pg8::Unit& u, int wr, int wc, int fr, int fq) const {
;     ...
;         const int colb = u.pn * 256 + wc * 32 + 8 * fq;
; #pragma unroll
;         for (int ai = 0; ai < 2; ++ai)
; #pragma unroll
;             for (int m = 0; m < 4; ++m) {
;                 const int rl = ai * 128 + wr * 64 + m * 16 + fr; const float r1 = S[rl];
;                 const size_t ro = (size_t)(u.pm * 256 + rl) * 1024 + colb;
;                 float q = 0.f;
; #pragma unroll
;                 for (int bj = 0; bj < 2; ++bj) {
;                     const v4u xw = *(const v4u*)(XB + ro + bj * 128);
;                     const v4f g0 = *(const v4f*)(gpost + colb + bj * 128), g1 = *(const v4f*)(gpost + colb + bj * 128 + 4);
;                     const pg8::f32x4 a0 = acc[ai][bj][m][0], a1 = acc[ai][bj][m][1];
;                     float v[8];
;                     v[0] = bflo(xw.x) + a0[0] * r1 * g0[0]; v[1] = bfhi(xw.x) + a0[1] * r1 * g0[1]; v[2] = bflo(xw.y) + a0[2] * r1 * g0[2]; v[3] = bfhi(xw.y) + a0[3] * r1 * g0[3];
;                     v[4] = bflo(xw.z) + a1[0] * r1 * g1[0]; v[5] = bfhi(xw.z) + a1[1] * r1 * g1[1]; v[6] = bflo(xw.w) + a1[2] * r1 * g1[2]; v[7] = bfhi(xw.w) + a1[3] * r1 * g1[3];
;                     q += ((v[0] * v[0] + v[1] * v[1]) + (v[2] * v[2] + v[3] * v[3])) + ((v[4] * v[4] + v[5] * v[5]) + (v[6] * v[6] + v[7] * v[7]));
;                     if (last) { *(v4f*)(OUT + ro + bj * 128) = (v4f){v[0], v[1], v[2], v[3]}; *(v4f*)(OUT + ro + bj * 128 + 4) = (v4f){v[4], v[5], v[6], v[7]}; }
;                     else { v4u w; w.x = pk2(v[0], v[1]); w.y = pk2(v[2], v[3]); w.z = pk2(v[4], v[5]); w.w = pk2(v[6], v[7]); *(v4u*)(XB + ro + bj * 128) = w; }
.LBB0_182:
	s_or_b64 exec, exec, s[24:25]
	v_add_u32_e32 v48, v152, v166
	s_waitcnt lgkmcnt(0)
	v_ashrrev_i32_e32 v49, 31, v48
	v_lshlrev_b64 v[50:51], 10, v[48:49]
	v_lshl_add_u64 v[54:55], v[50:51], 0, v[132:133]
	v_lshl_add_u64 v[50:51], v[54:55], 1, s[22:23]
	global_load_dwordx4 v[56:59], v[130:131], off offset:16
	global_load_dwordx4 v[60:63], v[130:131], off
	global_load_dwordx4 v[66:69], v[50:51], off
	global_load_dwordx4 v[206:209], v[50:51], off offset:256
	ds_read_b32 v52, v174
	s_mov_b64 s[24:25], -1
	s_and_b64 vcc, exec, s[44:45]
	s_waitcnt lgkmcnt(0)
	v_pk_mul_f32 v[44:45], v[44:45], v[52:53] op_sel_hi:[1,0]
	v_pk_mul_f32 v[46:47], v[46:47], v[52:53] op_sel_hi:[1,0]
	v_pk_mul_f32 v[40:41], v[40:41], v[52:53] op_sel_hi:[1,0]
	v_pk_mul_f32 v[42:43], v[42:43], v[52:53] op_sel_hi:[1,0]
	s_waitcnt vmcnt(0)
	v_lshlrev_b32_e32 v70, 16, v66
	v_and_b32_e32 v71, 0xffff0000, v66
	v_pk_fma_f32 v[44:45], v[60:61], v[44:45], v[70:71]
	v_lshlrev_b32_e32 v60, 16, v67
	v_and_b32_e32 v61, 0xffff0000, v67
	v_pk_fma_f32 v[46:47], v[62:63], v[46:47], v[60:61]
	v_lshlrev_b32_e32 v60, 16, v68
	v_and_b32_e32 v61, 0xffff0000, v68
	v_pk_fma_f32 v[40:41], v[56:57], v[40:41], v[60:61]
	v_lshlrev_b32_e32 v56, 16, v69
	v_and_b32_e32 v57, 0xffff0000, v69
	v_pk_fma_f32 v[42:43], v[58:59], v[42:43], v[56:57]
	s_cbranch_vccnz .LBB0_184
	v_cvt_pk_bf16_f32 v56, v44, v45
	v_cvt_pk_bf16_f32 v57, v46, v47
	v_cvt_pk_bf16_f32 v58, v40, v41
	v_cvt_pk_bf16_f32 v59, v42, v43
	s_mov_b64 s[24:25], 0
	global_store_dwordx4 v[50:51], v[56:59], off

; DI unsigned pk2(float lo, float hi) { f32x2_t v = {lo, hi}; bf16x2_t b = __builtin_convertvector(v, bf16x2_t); return __builtin_bit_cast(unsigned, b); }
; DI float bflo(unsigned u) { return __uint_as_float(u << 16); }
; DI float bfhi(unsigned u) { return __uint_as_float(u & 0xffff0000u); }
;     DI void operator()(pg8::f32x4 (&acc)[2][2][4][2], const pg8::Unit& u, int wr, int wc, int fr, int fq) const {
;     ...
;                 for (int bj = 0; bj < 2; ++bj) {
;                     const v4u xw = *(const v4u*)(XB + ro + bj * 128);
;                     const v4f g0 = *(const v4f*)(gpost + colb + bj * 128), g1 = *(const v4f*)(gpost + colb + bj * 128 + 4);
;                     const pg8::f32x4 a0 = acc[ai][bj][m][0], a1 = acc[ai][bj][m][1];
;                     float v[8];
;                     v[0] = bflo(xw.x) + a0[0] * r1 * g0[0]; v[1] = bfhi(xw.x) + a0[1] * r1 * g0[1]; v[2] = bflo(xw.y) + a0[2] * r1 * g0[2]; v[3] = bfhi(xw.y) + a0[3] * r1 * g0[3];
;                     v[4] = bflo(xw.z) + a1[0] * r1 * g1[0]; v[5] = bfhi(xw.z) + a1[1] * r1 * g1[1]; v[6] = bflo(xw.w) + a1[2] * r1 * g1[2]; v[7] = bfhi(xw.w) + a1[3] * r1 * g1[3];
;                     q += ((v[0] * v[0] + v[1] * v[1]) + (v[2] * v[2] + v[3] * v[3])) + ((v[4] * v[4] + v[5] * v[5]) + (v[6] * v[6] + v[7] * v[7]));
;                     if (last) { *(v4f*)(OUT + ro + bj * 128) = (v4f){v[0], v[1], v[2], v[3]}; *(v4f*)(OUT + ro + bj * 128 + 4) = (v4f){v[4], v[5], v[6], v[7]}; }
;                     else { v4u w; w.x = pk2(v[0], v[1]); w.y = pk2(v[2], v[3]); w.z = pk2(v[4], v[5]); w.w = pk2(v[6], v[7]); *(v4u*)(XB + ro + bj * 128) = w; }
.LBB0_186:
	global_load_dwordx4 v[60:63], v[130:131], off offset:512
	global_load_dwordx4 v[66:69], v[130:131], off offset:528
	v_mov_b32_e32 v53, v52
	v_pk_mul_f32 v[36:37], v[36:37], v[52:53]
	v_pk_mul_f32 v[38:39], v[38:39], v[52:53]
	v_pk_mul_f32 v[32:33], v[32:33], v[52:53]
	v_pk_mul_f32 v[34:35], v[34:35], v[52:53]
	s_and_b64 vcc, exec, s[44:45]
	s_mov_b64 s[24:25], -1
	s_waitcnt vmcnt(2)
	v_lshlrev_b32_e32 v52, 16, v206
	v_and_b32_e32 v53, 0xffff0000, v206
	v_lshlrev_b32_e32 v56, 16, v207
	v_and_b32_e32 v57, 0xffff0000, v207
	v_lshlrev_b32_e32 v70, 16, v208
	v_and_b32_e32 v71, 0xffff0000, v208
	v_lshlrev_b32_e32 v58, 16, v209
	v_and_b32_e32 v59, 0xffff0000, v209
	s_waitcnt vmcnt(1)
	v_pk_fma_f32 v[36:37], v[36:37], v[60:61], v[52:53]
	v_pk_fma_f32 v[38:39], v[38:39], v[62:63], v[56:57]
	s_waitcnt vmcnt(0)
	v_pk_fma_f32 v[32:33], v[32:33], v[66:67], v[70:71]
	v_pk_fma_f32 v[34:35], v[34:35], v[68:69], v[58:59]
	s_cbranch_vccnz .LBB0_188
	v_cvt_pk_bf16_f32 v56, v36, v37
	v_cvt_pk_bf16_f32 v57, v38, v39
	v_cvt_pk_bf16_f32 v58, v32, v33
	v_cvt_pk_bf16_f32 v59, v34, v35
	s_mov_b64 s[24:25], 0
	global_store_dwordx4 v[50:51], v[56:59], off offset:256

; DI unsigned pk2(float lo, float hi) { f32x2_t v = {lo, hi}; bf16x2_t b = __builtin_convertvector(v, bf16x2_t); return __builtin_bit_cast(unsigned, b); }
; DI float bflo(unsigned u) { return __uint_as_float(u << 16); }
; DI float bfhi(unsigned u) { return __uint_as_float(u & 0xffff0000u); }
;     DI void operator()(pg8::f32x4 (&acc)[2][2][4][2], const pg8::Unit& u, int wr, int wc, int fr, int fq) const {
;     ...
;         const int colb = u.pn * 256 + wc * 32 + 8 * fq;
; #pragma unroll
;         for (int ai = 0; ai < 2; ++ai)
; #pragma unroll
;             for (int m = 0; m < 4; ++m) {
;                 const int rl = ai * 128 + wr * 64 + m * 16 + fr; const float r1 = S[rl];
;                 const size_t ro = (size_t)(u.pm * 256 + rl) * 1024 + colb;
;                 float q = 0.f;
; #pragma unroll
;                 for (int bj = 0; bj < 2; ++bj) {
;                     const v4u xw = *(const v4u*)(XB + ro + bj * 128);
;                     const v4f g0 = *(const v4f*)(gpost + colb + bj * 128), g1 = *(const v4f*)(gpost + colb + bj * 128 + 4);
;                     const pg8::f32x4 a0 = acc[ai][bj][m][0], a1 = acc[ai][bj][m][1];
;                     float v[8];
;                     v[0] = bflo(xw.x) + a0[0] * r1 * g0[0]; v[1] = bfhi(xw.x) + a0[1] * r1 * g0[1]; v[2] = bflo(xw.y) + a0[2] * r1 * g0[2]; v[3] = bfhi(xw.y) + a0[3] * r1 * g0[3];
;                     v[4] = bflo(xw.z) + a1[0] * r1 * g1[0]; v[5] = bfhi(xw.z) + a1[1] * r1 * g1[1]; v[6] = bflo(xw.w) + a1[2] * r1 * g1[2]; v[7] = bfhi(xw.w) + a1[3] * r1 * g1[3];
;                     q += ((v[0] * v[0] + v[1] * v[1]) + (v[2] * v[2] + v[3] * v[3])) + ((v[4] * v[4] + v[5] * v[5]) + (v[6] * v[6] + v[7] * v[7]));
;                     if (last) { *(v4f*)(OUT + ro + bj * 128) = (v4f){v[0], v[1], v[2], v[3]}; *(v4f*)(OUT + ro + bj * 128 + 4) = (v4f){v[4], v[5], v[6], v[7]}; }
;                     else { v4u w; w.x = pk2(v[0], v[1]); w.y = pk2(v[2], v[3]); w.z = pk2(v[4], v[5]); w.w = pk2(v[6], v[7]); *(v4u*)(XB + ro + bj * 128) = w; }
.LBB0_192:
	s_or_b64 exec, exec, s[24:25]
	v_add_u32_e32 v32, v152, v167
	s_waitcnt lgkmcnt(0)
	v_ashrrev_i32_e32 v33, 31, v32
	v_lshlrev_b64 v[34:35], 10, v[32:33]
	v_lshl_add_u64 v[38:39], v[34:35], 0, v[132:133]
	v_lshl_add_u64 v[34:35], v[38:39], 1, s[22:23]
	ds_read_b32 v36, v176
	global_load_dwordx4 v[40:43], v[34:35], off
	global_load_dwordx4 v[206:209], v[34:35], off offset:256
	global_load_dwordx4 v[44:47], v[130:131], off offset:16
	global_load_dwordx4 v[48:51], v[130:131], off
	s_mov_b64 s[24:25], -1
	s_and_b64 vcc, exec, s[44:45]
	s_waitcnt lgkmcnt(0)
	v_pk_mul_f32 v[30:31], v[30:31], v[36:37] op_sel_hi:[1,0]
	v_pk_mul_f32 v[24:25], v[24:25], v[36:37] op_sel_hi:[1,0]
	v_pk_mul_f32 v[28:29], v[28:29], v[36:37] op_sel_hi:[1,0]
	v_pk_mul_f32 v[26:27], v[26:27], v[36:37] op_sel_hi:[1,0]
	s_waitcnt vmcnt(2)
	v_lshlrev_b32_e32 v52, 16, v40
	v_and_b32_e32 v53, 0xffff0000, v40
	v_lshlrev_b32_e32 v40, 16, v41
	v_and_b32_e32 v41, 0xffff0000, v41
	s_waitcnt vmcnt(0)
	v_pk_fma_f32 v[30:31], v[30:31], v[50:51], v[40:41]
	v_lshlrev_b32_e32 v40, 16, v42
	v_and_b32_e32 v41, 0xffff0000, v42
	v_pk_fma_f32 v[24:25], v[24:25], v[44:45], v[40:41]
	v_lshlrev_b32_e32 v40, 16, v43
	v_and_b32_e32 v41, 0xffff0000, v43
	v_pk_fma_f32 v[28:29], v[28:29], v[48:49], v[52:53]
	v_pk_fma_f32 v[26:27], v[26:27], v[46:47], v[40:41]
	s_cbranch_vccnz .LBB0_194
	v_cvt_pk_bf16_f32 v40, v28, v29
	v_cvt_pk_bf16_f32 v41, v30, v31
	v_cvt_pk_bf16_f32 v42, v24, v25
	v_cvt_pk_bf16_f32 v43, v26, v27
	s_mov_b64 s[24:25], 0
	global_store_dwordx4 v[34:35], v[40:43], off

; DI unsigned pk2(float lo, float hi) { f32x2_t v = {lo, hi}; bf16x2_t b = __builtin_convertvector(v, bf16x2_t); return __builtin_bit_cast(unsigned, b); }
; DI float bflo(unsigned u) { return __uint_as_float(u << 16); }
; DI float bfhi(unsigned u) { return __uint_as_float(u & 0xffff0000u); }
;     DI void operator()(pg8::f32x4 (&acc)[2][2][4][2], const pg8::Unit& u, int wr, int wc, int fr, int fq) const {
;     ...
;                 for (int bj = 0; bj < 2; ++bj) {
;                     const v4u xw = *(const v4u*)(XB + ro + bj * 128);
;                     const v4f g0 = *(const v4f*)(gpost + colb + bj * 128), g1 = *(const v4f*)(gpost + colb + bj * 128 + 4);
;                     const pg8::f32x4 a0 = acc[ai][bj][m][0], a1 = acc[ai][bj][m][1];
;                     float v[8];
;                     v[0] = bflo(xw.x) + a0[0] * r1 * g0[0]; v[1] = bfhi(xw.x) + a0[1] * r1 * g0[1]; v[2] = bflo(xw.y) + a0[2] * r1 * g0[2]; v[3] = bfhi(xw.y) + a0[3] * r1 * g0[3];
;                     v[4] = bflo(xw.z) + a1[0] * r1 * g1[0]; v[5] = bfhi(xw.z) + a1[1] * r1 * g1[1]; v[6] = bflo(xw.w) + a1[2] * r1 * g1[2]; v[7] = bfhi(xw.w) + a1[3] * r1 * g1[3];
;                     q += ((v[0] * v[0] + v[1] * v[1]) + (v[2] * v[2] + v[3] * v[3])) + ((v[4] * v[4] + v[5] * v[5]) + (v[6] * v[6] + v[7] * v[7]));
;                     if (last) { *(v4f*)(OUT + ro + bj * 128) = (v4f){v[0], v[1], v[2], v[3]}; *(v4f*)(OUT + ro + bj * 128 + 4) = (v4f){v[4], v[5], v[6], v[7]}; }
;                     else { v4u w; w.x = pk2(v[0], v[1]); w.y = pk2(v[2], v[3]); w.z = pk2(v[4], v[5]); w.w = pk2(v[6], v[7]); *(v4u*)(XB + ro + bj * 128) = w; }
.LBB0_196:
	global_load_dwordx4 v[44:47], v[130:131], off offset:512
	global_load_dwordx4 v[48:51], v[130:131], off offset:528
	v_mov_b32_e32 v37, v36
	v_pk_mul_f32 v[20:21], v[20:21], v[36:37]
	v_pk_mul_f32 v[22:23], v[22:23], v[36:37]
	v_pk_mul_f32 v[16:17], v[16:17], v[36:37]
	v_pk_mul_f32 v[18:19], v[18:19], v[36:37]
	s_and_b64 vcc, exec, s[44:45]
	s_mov_b64 s[24:25], -1
	s_waitcnt vmcnt(2)
	v_lshlrev_b32_e32 v36, 16, v206
	v_and_b32_e32 v37, 0xffff0000, v206
	v_lshlrev_b32_e32 v40, 16, v207
	v_and_b32_e32 v41, 0xffff0000, v207
	v_lshlrev_b32_e32 v52, 16, v208
	v_and_b32_e32 v53, 0xffff0000, v208
	v_lshlrev_b32_e32 v42, 16, v209
	v_and_b32_e32 v43, 0xffff0000, v209
	s_waitcnt vmcnt(1)
	v_pk_fma_f32 v[20:21], v[20:21], v[44:45], v[36:37]
	v_pk_fma_f32 v[22:23], v[22:23], v[46:47], v[40:41]
	s_waitcnt vmcnt(0)
	v_pk_fma_f32 v[16:17], v[16:17], v[48:49], v[52:53]
	v_pk_fma_f32 v[18:19], v[18:19], v[50:51], v[42:43]
	s_cbranch_vccnz .LBB0_198
	v_cvt_pk_bf16_f32 v40, v20, v21
	v_cvt_pk_bf16_f32 v41, v22, v23
	v_cvt_pk_bf16_f32 v42, v16, v17
	v_cvt_pk_bf16_f32 v43, v18, v19
	s_mov_b64 s[24:25], 0
	global_store_dwordx4 v[34:35], v[40:43], off offset:256

; DI unsigned pk2(float lo, float hi) { f32x2_t v = {lo, hi}; bf16x2_t b = __builtin_convertvector(v, bf16x2_t); return __builtin_bit_cast(unsigned, b); }
; DI float bflo(unsigned u) { return __uint_as_float(u << 16); }
; DI float bfhi(unsigned u) { return __uint_as_float(u & 0xffff0000u); }
;     DI void operator()(pg8::f32x4 (&acc)[2][2][4][2], const pg8::Unit& u, int wr, int wc, int fr, int fq) const {
;     ...
;         const int colb = u.pn * 256 + wc * 32 + 8 * fq;
; #pragma unroll
;         for (int ai = 0; ai < 2; ++ai)
; #pragma unroll
;             for (int m = 0; m < 4; ++m) {
;                 const int rl = ai * 128 + wr * 64 + m * 16 + fr; const float r1 = S[rl];
;                 const size_t ro = (size_t)(u.pm * 256 + rl) * 1024 + colb;
;                 float q = 0.f;
; #pragma unroll
;                 for (int bj = 0; bj < 2; ++bj) {
;                     const v4u xw = *(const v4u*)(XB + ro + bj * 128);
;                     const v4f g0 = *(const v4f*)(gpost + colb + bj * 128), g1 = *(const v4f*)(gpost + colb + bj * 128 + 4);
;                     const pg8::f32x4 a0 = acc[ai][bj][m][0], a1 = acc[ai][bj][m][1];
;                     float v[8];
;                     v[0] = bflo(xw.x) + a0[0] * r1 * g0[0]; v[1] = bfhi(xw.x) + a0[1] * r1 * g0[1]; v[2] = bflo(xw.y) + a0[2] * r1 * g0[2]; v[3] = bfhi(xw.y) + a0[3] * r1 * g0[3];
;                     v[4] = bflo(xw.z) + a1[0] * r1 * g1[0]; v[5] = bfhi(xw.z) + a1[1] * r1 * g1[1]; v[6] = bflo(xw.w) + a1[2] * r1 * g1[2]; v[7] = bfhi(xw.w) + a1[3] * r1 * g1[3];
;                     q += ((v[0] * v[0] + v[1] * v[1]) + (v[2] * v[2] + v[3] * v[3])) + ((v[4] * v[4] + v[5] * v[5]) + (v[6] * v[6] + v[7] * v[7]));
;                     if (last) { *(v4f*)(OUT + ro + bj * 128) = (v4f){v[0], v[1], v[2], v[3]}; *(v4f*)(OUT + ro + bj * 128 + 4) = (v4f){v[4], v[5], v[6], v[7]}; }
;                     else { v4u w; w.x = pk2(v[0], v[1]); w.y = pk2(v[2], v[3]); w.z = pk2(v[4], v[5]); w.w = pk2(v[6], v[7]); *(v4u*)(XB + ro + bj * 128) = w; }
.LBB0_202:
	s_or_b64 exec, exec, s[24:25]
	v_add_u32_e32 v16, v152, v168
	s_waitcnt lgkmcnt(0)
	v_ashrrev_i32_e32 v17, 31, v16
	v_lshlrev_b64 v[18:19], 10, v[16:17]
	v_lshl_add_u64 v[22:23], v[18:19], 0, v[132:133]
	v_lshl_add_u64 v[18:19], v[22:23], 1, s[22:23]
	global_load_dwordx4 v[24:27], v[130:131], off offset:16
	global_load_dwordx4 v[28:31], v[130:131], off
	global_load_dwordx4 v[32:35], v[18:19], off
	global_load_dwordx4 v[206:209], v[18:19], off offset:256
	ds_read_b32 v20, v177
	s_mov_b64 s[22:23], -1
	s_and_b64 vcc, exec, s[44:45]
	s_waitcnt lgkmcnt(0)
	v_pk_mul_f32 v[12:13], v[12:13], v[20:21] op_sel_hi:[1,0]
	v_pk_mul_f32 v[14:15], v[14:15], v[20:21] op_sel_hi:[1,0]
	v_pk_mul_f32 v[8:9], v[8:9], v[20:21] op_sel_hi:[1,0]
	v_pk_mul_f32 v[10:11], v[10:11], v[20:21] op_sel_hi:[1,0]
	s_waitcnt vmcnt(0)
	v_lshlrev_b32_e32 v36, 16, v32
	v_and_b32_e32 v37, 0xffff0000, v32
	v_pk_fma_f32 v[12:13], v[28:29], v[12:13], v[36:37]
	v_lshlrev_b32_e32 v28, 16, v33
	v_and_b32_e32 v29, 0xffff0000, v33
	v_pk_fma_f32 v[14:15], v[30:31], v[14:15], v[28:29]
	v_lshlrev_b32_e32 v28, 16, v34
	v_and_b32_e32 v29, 0xffff0000, v34
	v_pk_fma_f32 v[8:9], v[24:25], v[8:9], v[28:29]
	v_lshlrev_b32_e32 v24, 16, v35
	v_and_b32_e32 v25, 0xffff0000, v35
	v_pk_fma_f32 v[10:11], v[26:27], v[10:11], v[24:25]
	s_cbranch_vccnz .LBB0_204
	v_cvt_pk_bf16_f32 v24, v12, v13
	v_cvt_pk_bf16_f32 v25, v14, v15
	v_cvt_pk_bf16_f32 v26, v8, v9
	v_cvt_pk_bf16_f32 v27, v10, v11
	s_mov_b64 s[22:23], 0
	global_store_dwordx4 v[18:19], v[24:27], off

; DI unsigned pk2(float lo, float hi) { f32x2_t v = {lo, hi}; bf16x2_t b = __builtin_convertvector(v, bf16x2_t); return __builtin_bit_cast(unsigned, b); }
; DI float bflo(unsigned u) { return __uint_as_float(u << 16); }
; DI float bfhi(unsigned u) { return __uint_as_float(u & 0xffff0000u); }
;     DI void operator()(pg8::f32x4 (&acc)[2][2][4][2], const pg8::Unit& u, int wr, int wc, int fr, int fq) const {
;     ...
;                 for (int bj = 0; bj < 2; ++bj) {
;                     const v4u xw = *(const v4u*)(XB + ro + bj * 128);
;                     const v4f g0 = *(const v4f*)(gpost + colb + bj * 128), g1 = *(const v4f*)(gpost + colb + bj * 128 + 4);
;                     const pg8::f32x4 a0 = acc[ai][bj][m][0], a1 = acc[ai][bj][m][1];
;                     float v[8];
;                     v[0] = bflo(xw.x) + a0[0] * r1 * g0[0]; v[1] = bfhi(xw.x) + a0[1] * r1 * g0[1]; v[2] = bflo(xw.y) + a0[2] * r1 * g0[2]; v[3] = bfhi(xw.y) + a0[3] * r1 * g0[3];
;                     v[4] = bflo(xw.z) + a1[0] * r1 * g1[0]; v[5] = bfhi(xw.z) + a1[1] * r1 * g1[1]; v[6] = bflo(xw.w) + a1[2] * r1 * g1[2]; v[7] = bfhi(xw.w) + a1[3] * r1 * g1[3];
;                     q += ((v[0] * v[0] + v[1] * v[1]) + (v[2] * v[2] + v[3] * v[3])) + ((v[4] * v[4] + v[5] * v[5]) + (v[6] * v[6] + v[7] * v[7]));
;                     if (last) { *(v4f*)(OUT + ro + bj * 128) = (v4f){v[0], v[1], v[2], v[3]}; *(v4f*)(OUT + ro + bj * 128 + 4) = (v4f){v[4], v[5], v[6], v[7]}; }
;                     else { v4u w; w.x = pk2(v[0], v[1]); w.y = pk2(v[2], v[3]); w.z = pk2(v[4], v[5]); w.w = pk2(v[6], v[7]); *(v4u*)(XB + ro + bj * 128) = w; }
.LBB0_206:
	global_load_dwordx4 v[28:31], v[130:131], off offset:512
	global_load_dwordx4 v[32:35], v[130:131], off offset:528
	v_mov_b32_e32 v21, v20
	v_pk_mul_f32 v[4:5], v[4:5], v[20:21]
	v_pk_mul_f32 v[6:7], v[6:7], v[20:21]
	v_pk_mul_f32 v[0:1], v[0:1], v[20:21]
	v_pk_mul_f32 v[2:3], v[2:3], v[20:21]
	s_and_b64 vcc, exec, s[44:45]
	s_mov_b64 s[22:23], -1
	s_waitcnt vmcnt(2)
	v_lshlrev_b32_e32 v20, 16, v206
	v_and_b32_e32 v21, 0xffff0000, v206
	v_lshlrev_b32_e32 v24, 16, v207
	v_and_b32_e32 v25, 0xffff0000, v207
	v_lshlrev_b32_e32 v36, 16, v208
	v_and_b32_e32 v37, 0xffff0000, v208
	v_lshlrev_b32_e32 v26, 16, v209
	v_and_b32_e32 v27, 0xffff0000, v209
	s_waitcnt vmcnt(1)
	v_pk_fma_f32 v[4:5], v[4:5], v[28:29], v[20:21]
	v_pk_fma_f32 v[6:7], v[6:7], v[30:31], v[24:25]
	s_waitcnt vmcnt(0)
	v_pk_fma_f32 v[0:1], v[0:1], v[32:33], v[36:37]
	v_pk_fma_f32 v[2:3], v[2:3], v[34:35], v[26:27]
	s_cbranch_vccnz .LBB0_208
	v_cvt_pk_bf16_f32 v24, v4, v5
	v_cvt_pk_bf16_f32 v25, v6, v7
	v_cvt_pk_bf16_f32 v26, v0, v1
	v_cvt_pk_bf16_f32 v27, v2, v3
	s_mov_b64 s[22:23], 0
	global_store_dwordx4 v[18:19], v[24:27], off offset:256

; DI unsigned pk2(float lo, float hi) { f32x2_t v = {lo, hi}; bf16x2_t b = __builtin_convertvector(v, bf16x2_t); return __builtin_bit_cast(unsigned, b); }
; DI float bflo(unsigned u) { return __uint_as_float(u << 16); }
; DI float bfhi(unsigned u) { return __uint_as_float(u & 0xffff0000u); }
;     DI void operator()(pg8::f32x4 (&acc)[2][2][4][2], const pg8::Unit& u, int wr, int wc, int fr, int fq) const {
;     ...
;         const int colb = u.pn * 256 + wc * 32 + 8 * fq;
; #pragma unroll
;         for (int ai = 0; ai < 2; ++ai)
; #pragma unroll
;             for (int m = 0; m < 4; ++m) {
;                 const int rl = ai * 128 + wr * 64 + m * 16 + fr; const float r1 = S[rl];
;                 const size_t ro = (size_t)(u.pm * 256 + rl) * 1024 + colb;
;                 float q = 0.f;
; #pragma unroll
;                 for (int bj = 0; bj < 2; ++bj) {
;                     const v4u xw = *(const v4u*)(XB + ro + bj * 128);
;                     const v4f g0 = *(const v4f*)(gpost + colb + bj * 128), g1 = *(const v4f*)(gpost + colb + bj * 128 + 4);
;                     const pg8::f32x4 a0 = acc[ai][bj][m][0], a1 = acc[ai][bj][m][1];
;                     float v[8];
;                     v[0] = bflo(xw.x) + a0[0] * r1 * g0[0]; v[1] = bfhi(xw.x) + a0[1] * r1 * g0[1]; v[2] = bflo(xw.y) + a0[2] * r1 * g0[2]; v[3] = bfhi(xw.y) + a0[3] * r1 * g0[3];
;                     v[4] = bflo(xw.z) + a1[0] * r1 * g1[0]; v[5] = bfhi(xw.z) + a1[1] * r1 * g1[1]; v[6] = bflo(xw.w) + a1[2] * r1 * g1[2]; v[7] = bfhi(xw.w) + a1[3] * r1 * g1[3];
;                     q += ((v[0] * v[0] + v[1] * v[1]) + (v[2] * v[2] + v[3] * v[3])) + ((v[4] * v[4] + v[5] * v[5]) + (v[6] * v[6] + v[7] * v[7]));
;                     if (last) { *(v4f*)(OUT + ro + bj * 128) = (v4f){v[0], v[1], v[2], v[3]}; *(v4f*)(OUT + ro + bj * 128 + 4) = (v4f){v[4], v[5], v[6], v[7]}; }
;                     else { v4u w; w.x = pk2(v[0], v[1]); w.y = pk2(v[2], v[3]); w.z = pk2(v[4], v[5]); w.w = pk2(v[6], v[7]); *(v4u*)(XB + ro + bj * 128) = w; }
;                 }
;                 q += __shfl_xor(q, 16); q += __shfl_xor(q, 32);
;                 if (fq == 0) slots2[(size_t)(u.pm * 256 + rl) * 16 + u.pn * 4 + wc] = q;
;                 if (m & 1) asm volatile("" ::: "memory");
;             }
.LBB0_426:
	s_or_b64 exec, exec, s[24:25]
	v_readlane_b32 s0, v255, 7
	v_lshl_or_b32 v0, s20, 8, v162
	v_readlane_b32 s1, v255, 8
	v_ashrrev_i32_e32 v1, 31, v0
	v_add_u32_e32 v4, v150, v160
	s_lshl_b64 s[22:23], s[0:1], 2
	v_lshl_add_u64 v[2:3], v[0:1], 1, s[26:27]
	s_mov_b64 s[24:25], 0x7000000
	v_ashrrev_i32_e32 v5, 31, v4
	s_add_u32 s22, s28, s22
	v_lshl_add_u64 v[2:3], v[2:3], 0, s[24:25]
	v_lshlrev_b64 v[6:7], 11, v[4:5]
	s_addc_u32 s23, s29, s23
	s_waitcnt lgkmcnt(0)
	s_barrier
	v_lshl_add_u64 v[6:7], v[2:3], 0, v[6:7]
	v_lshl_add_u64 v[0:1], v[0:1], 2, s[22:23]
	ds_read_b32 v64, v174
	global_load_dwordx4 v[152:155], v[6:7], off
	global_load_dwordx4 v[206:209], v[6:7], off offset:256
	global_load_dwordx4 v[156:159], v[0:1], off offset:16
	global_load_dwordx4 v[180:183], v[0:1], off
	s_lshl_b32 s20, s20, 2
	s_ashr_i32 s21, s20, 31
	s_lshl_b64 s[20:21], s[20:21], 2
	s_waitcnt lgkmcnt(0)
	v_pk_mul_f32 v[148:149], v[148:149], v[64:65] op_sel_hi:[1,0]
	v_pk_mul_f32 v[144:145], v[144:145], v[64:65] op_sel_hi:[1,0]
	v_pk_mul_f32 v[146:147], v[146:147], v[64:65] op_sel_hi:[1,0]
	v_pk_mul_f32 v[130:131], v[130:131], v[64:65] op_sel_hi:[1,0]
	v_pk_mul_f32 v[126:127], v[126:127], v[64:65] op_sel_hi:[1,0]
	v_pk_mul_f32 v[124:125], v[124:125], v[64:65] op_sel_hi:[1,0]
	v_pk_mul_f32 v[122:123], v[122:123], v[64:65] op_sel_hi:[1,0]
	v_pk_mul_f32 v[128:129], v[128:129], v[64:65] op_sel_hi:[1,0]
	s_add_u32 s8, s26, s20
	s_addc_u32 s10, s27, s21
	s_add_u32 s8, s8, s50
	s_addc_u32 s10, s10, 0
	s_add_u32 s20, s8, 0x1c900000
	s_addc_u32 s21, s10, 0
	s_waitcnt vmcnt(0)
	v_lshlrev_b32_e32 v172, 16, v152
	v_and_b32_e32 v173, 0xffff0000, v152
	v_pk_fma_f32 v[172:173], v[148:149], v[180:181], v[172:173]
	v_lshlrev_b32_e32 v148, 16, v153
	v_and_b32_e32 v149, 0xffff0000, v153
	v_pk_fma_f32 v[180:181], v[144:145], v[182:183], v[148:149]
	v_lshlrev_b32_e32 v144, 16, v154
	v_and_b32_e32 v145, 0xffff0000, v154
	v_pk_fma_f32 v[156:157], v[146:147], v[156:157], v[144:145]
	v_lshlrev_b32_e32 v144, 16, v155
	v_and_b32_e32 v145, 0xffff0000, v155
	v_pk_fma_f32 v[158:159], v[130:131], v[158:159], v[144:145]
	v_cvt_pk_bf16_f32 v152, v172, v173
	v_cvt_pk_bf16_f32 v153, v180, v181
	v_cvt_pk_bf16_f32 v154, v156, v157
	v_cvt_pk_bf16_f32 v155, v158, v159
	global_store_dwordx4 v[6:7], v[152:155], off
	v_pk_mul_f32 v[144:145], v[180:181], v[180:181]
	v_pk_mul_f32 v[146:147], v[156:157], v[156:157]
	v_pk_mul_f32 v[148:149], v[158:159], v[158:159]
	global_load_dwordx4 v[156:159], v[0:1], off offset:528
	global_load_dwordx4 v[180:183], v[0:1], off offset:512
	v_pk_mul_f32 v[130:131], v[172:173], v[172:173]
	v_add_f32_e32 v64, v148, v149
	v_add_f32_e32 v146, v146, v147
	v_add_f32_e32 v144, v144, v145
	v_add_f32_e32 v130, v130, v131
	v_add_f32_e32 v64, v146, v64
	v_add_f32_e32 v130, v130, v144
	v_add_f32_e32 v64, v130, v64
	s_waitcnt vmcnt(2)
	v_lshlrev_b32_e32 v172, 16, v206
	v_and_b32_e32 v173, 0xffff0000, v206
	v_lshlrev_b32_e32 v152, 16, v207
	v_and_b32_e32 v153, 0xffff0000, v207
	s_waitcnt vmcnt(0)
	v_pk_fma_f32 v[126:127], v[126:127], v[182:183], v[152:153]
	v_lshlrev_b32_e32 v152, 16, v208
	v_and_b32_e32 v153, 0xffff0000, v208
	v_pk_fma_f32 v[124:125], v[124:125], v[156:157], v[152:153]
	v_lshlrev_b32_e32 v152, 16, v209
	v_and_b32_e32 v153, 0xffff0000, v209
	v_pk_fma_f32 v[152:153], v[122:123], v[158:159], v[152:153]
	v_pk_fma_f32 v[128:129], v[128:129], v[180:181], v[172:173]
	v_pk_mul_f32 v[156:157], v[124:125], v[124:125]
	v_pk_mul_f32 v[158:159], v[152:153], v[152:153]
	v_pk_mul_f32 v[122:123], v[128:129], v[128:129]
	v_pk_mul_f32 v[154:155], v[126:127], v[126:127]
	v_add_f32_e32 v130, v158, v159
	v_add_f32_e32 v131, v156, v157
	v_add_f32_e32 v130, v131, v130
	v_add_f32_e32 v131, v154, v155
	v_add_f32_e32 v122, v122, v123
	v_add_f32_e32 v122, v122, v131
	v_add_f32_e32 v122, v122, v130
	v_add_f32_e32 v64, v64, v122
	v_cvt_pk_bf16_f32 v122, v128, v129
	v_cvt_pk_bf16_f32 v123, v126, v127
	v_cvt_pk_bf16_f32 v124, v124, v125
	v_cvt_pk_bf16_f32 v125, v152, v153
	global_store_dwordx4 v[6:7], v[122:125], off offset:256
	ds_bpermute_b32 v6, v177, v64
	s_waitcnt lgkmcnt(0)
	v_add_f32_e32 v6, v64, v6
	ds_bpermute_b32 v7, v178, v6
	s_and_saveexec_b64 s[22:23], s[38:39]
	s_cbranch_execz .LBB0_428
	v_lshlrev_b64 v[4:5], 6, v[4:5]
	v_lshl_add_u64 v[4:5], s[20:21], 0, v[4:5]
	s_waitcnt lgkmcnt(0)
	v_add_f32_e32 v6, v6, v7
	global_store_dword v[4:5], v6, off
; DI unsigned pk2(float lo, float hi) { f32x2_t v = {lo, hi}; bf16x2_t b = __builtin_convertvector(v, bf16x2_t); return __builtin_bit_cast(unsigned, b); }
; DI float bflo(unsigned u) { return __uint_as_float(u << 16); }
; DI float bfhi(unsigned u) { return __uint_as_float(u & 0xffff0000u); }
;     DI void operator()(pg8::f32x4 (&acc)[2][2][4][2], const pg8::Unit& u, int wr, int wc, int fr, int fq) const {
;     ...
;         const int colb = u.pn * 256 + wc * 32 + 8 * fq;
; #pragma unroll
;         for (int ai = 0; ai < 2; ++ai)
; #pragma unroll
;             for (int m = 0; m < 4; ++m) {
;                 const int rl = ai * 128 + wr * 64 + m * 16 + fr; const float r1 = S[rl];
;                 const size_t ro = (size_t)(u.pm * 256 + rl) * 1024 + colb;
;                 float q = 0.f;
; #pragma unroll
;                 for (int bj = 0; bj < 2; ++bj) {
;                     const v4u xw = *(const v4u*)(XB + ro + bj * 128);
;                     const v4f g0 = *(const v4f*)(gpost + colb + bj * 128), g1 = *(const v4f*)(gpost + colb + bj * 128 + 4);
;                     const pg8::f32x4 a0 = acc[ai][bj][m][0], a1 = acc[ai][bj][m][1];
;                     float v[8];
;                     v[0] = bflo(xw.x) + a0[0] * r1 * g0[0]; v[1] = bfhi(xw.x) + a0[1] * r1 * g0[1]; v[2] = bflo(xw.y) + a0[2] * r1 * g0[2]; v[3] = bfhi(xw.y) + a0[3] * r1 * g0[3];
;                     v[4] = bflo(xw.z) + a1[0] * r1 * g1[0]; v[5] = bfhi(xw.z) + a1[1] * r1 * g1[1]; v[6] = bflo(xw.w) + a1[2] * r1 * g1[2]; v[7] = bfhi(xw.w) + a1[3] * r1 * g1[3];
;                     q += ((v[0] * v[0] + v[1] * v[1]) + (v[2] * v[2] + v[3] * v[3])) + ((v[4] * v[4] + v[5] * v[5]) + (v[6] * v[6] + v[7] * v[7]));
;                     if (last) { *(v4f*)(OUT + ro + bj * 128) = (v4f){v[0], v[1], v[2], v[3]}; *(v4f*)(OUT + ro + bj * 128 + 4) = (v4f){v[4], v[5], v[6], v[7]}; }
;                     else { v4u w; w.x = pk2(v[0], v[1]); w.y = pk2(v[2], v[3]); w.z = pk2(v[4], v[5]); w.w = pk2(v[6], v[7]); *(v4u*)(XB + ro + bj * 128) = w; }
;                 }
;                 q += __shfl_xor(q, 16); q += __shfl_xor(q, 32);
;                 if (fq == 0) slots2[(size_t)(u.pm * 256 + rl) * 16 + u.pn * 4 + wc] = q;
;                 if (m & 1) asm volatile("" ::: "memory");
;             }
.LBB0_428:
	s_or_b64 exec, exec, s[22:23]
	v_lshl_add_u32 v4, v164, 2, s68
	global_load_dwordx4 v[122:125], v[0:1], off offset:16
	global_load_dwordx4 v[126:129], v[0:1], off
	ds_read_b32 v64, v4
	v_add_u32_e32 v4, v150, v164
	v_ashrrev_i32_e32 v5, 31, v4
	s_waitcnt lgkmcnt(1)
	v_lshlrev_b64 v[6:7], 11, v[4:5]
	v_lshl_add_u64 v[6:7], v[2:3], 0, v[6:7]
	global_load_dwordx4 v[144:147], v[6:7], off
	global_load_dwordx4 v[206:209], v[6:7], off offset:256
	s_waitcnt lgkmcnt(0)
	v_pk_mul_f32 v[120:121], v[120:121], v[64:65] op_sel_hi:[1,0]
	v_pk_mul_f32 v[116:117], v[116:117], v[64:65] op_sel_hi:[1,0]
	v_pk_mul_f32 v[118:119], v[118:119], v[64:65] op_sel_hi:[1,0]
	v_pk_mul_f32 v[114:115], v[114:115], v[64:65] op_sel_hi:[1,0]
	v_pk_mul_f32 v[110:111], v[110:111], v[64:65] op_sel_hi:[1,0]
	v_pk_mul_f32 v[108:109], v[108:109], v[64:65] op_sel_hi:[1,0]
	v_pk_mul_f32 v[106:107], v[106:107], v[64:65] op_sel_hi:[1,0]
	v_pk_mul_f32 v[112:113], v[112:113], v[64:65] op_sel_hi:[1,0]
	s_waitcnt vmcnt(0)
	v_lshlrev_b32_e32 v130, 16, v144
	v_and_b32_e32 v131, 0xffff0000, v144
	v_pk_fma_f32 v[126:127], v[126:127], v[120:121], v[130:131]
	v_lshlrev_b32_e32 v120, 16, v145
	v_and_b32_e32 v121, 0xffff0000, v145
	v_pk_fma_f32 v[128:129], v[128:129], v[116:117], v[120:121]
	v_lshlrev_b32_e32 v116, 16, v146
	v_and_b32_e32 v117, 0xffff0000, v146
	v_pk_fma_f32 v[130:131], v[122:123], v[118:119], v[116:117]
	v_lshlrev_b32_e32 v116, 16, v147
	v_and_b32_e32 v117, 0xffff0000, v147
	v_pk_fma_f32 v[144:145], v[124:125], v[114:115], v[116:117]
	v_cvt_pk_bf16_f32 v122, v126, v127
	v_cvt_pk_bf16_f32 v123, v128, v129
	v_cvt_pk_bf16_f32 v124, v130, v131
	v_cvt_pk_bf16_f32 v125, v144, v145
	global_store_dwordx4 v[6:7], v[122:125], off
	v_pk_mul_f32 v[114:115], v[126:127], v[126:127]
	v_pk_mul_f32 v[116:117], v[128:129], v[128:129]
	v_pk_mul_f32 v[120:121], v[144:145], v[144:145]
	global_load_dwordx4 v[126:129], v[0:1], off offset:528
	global_load_dwordx4 v[144:147], v[0:1], off offset:512
	v_pk_mul_f32 v[118:119], v[130:131], v[130:131]
	v_add_f32_e32 v64, v120, v121
	v_add_f32_e32 v118, v118, v119
	v_add_f32_e32 v116, v116, v117
	v_add_f32_e32 v114, v114, v115
	v_add_f32_e32 v64, v118, v64
	v_add_f32_e32 v114, v114, v116
	v_add_f32_e32 v64, v114, v64
	s_waitcnt vmcnt(2)
	v_lshlrev_b32_e32 v130, 16, v206
	v_and_b32_e32 v131, 0xffff0000, v206
	v_lshlrev_b32_e32 v122, 16, v207
	v_and_b32_e32 v123, 0xffff0000, v207
	s_waitcnt vmcnt(0)
	v_pk_fma_f32 v[110:111], v[110:111], v[146:147], v[122:123]
	v_lshlrev_b32_e32 v122, 16, v208
	v_and_b32_e32 v123, 0xffff0000, v208
	v_pk_fma_f32 v[108:109], v[108:109], v[126:127], v[122:123]
	v_lshlrev_b32_e32 v122, 16, v209
	v_and_b32_e32 v123, 0xffff0000, v209
	v_pk_fma_f32 v[122:123], v[106:107], v[128:129], v[122:123]
	v_pk_fma_f32 v[112:113], v[112:113], v[144:145], v[130:131]
	v_pk_mul_f32 v[126:127], v[108:109], v[108:109]
	v_pk_mul_f32 v[128:129], v[122:123], v[122:123]
	v_pk_mul_f32 v[106:107], v[112:113], v[112:113]
	v_pk_mul_f32 v[124:125], v[110:111], v[110:111]
	v_add_f32_e32 v114, v128, v129
	v_add_f32_e32 v115, v126, v127
	v_add_f32_e32 v114, v115, v114
	v_add_f32_e32 v115, v124, v125
	v_add_f32_e32 v106, v106, v107
	v_add_f32_e32 v106, v106, v115
	v_add_f32_e32 v106, v106, v114
	v_add_f32_e32 v64, v64, v106
	v_cvt_pk_bf16_f32 v106, v112, v113
	v_cvt_pk_bf16_f32 v107, v110, v111
	v_cvt_pk_bf16_f32 v108, v108, v109
	v_cvt_pk_bf16_f32 v109, v122, v123
	global_store_dwordx4 v[6:7], v[106:109], off offset:256
	ds_bpermute_b32 v6, v177, v64
	s_waitcnt lgkmcnt(0)
	v_add_f32_e32 v6, v64, v6
	ds_bpermute_b32 v7, v178, v6
	s_and_saveexec_b64 s[22:23], s[38:39]
	s_cbranch_execz .LBB0_430
	v_lshlrev_b64 v[4:5], 6, v[4:5]
	v_lshl_add_u64 v[4:5], s[20:21], 0, v[4:5]
	s_waitcnt lgkmcnt(0)
	v_add_f32_e32 v6, v6, v7
	global_store_dword v[4:5], v6, off
.LBB0_430:
	s_or_b64 exec, exec, s[22:23]
	v_lshl_add_u32 v4, v165, 2, s68
	ds_read_b32 v64, v4
	v_add_u32_e32 v4, v150, v165
	v_ashrrev_i32_e32 v5, 31, v4
	s_waitcnt lgkmcnt(1)
	v_lshlrev_b64 v[6:7], 11, v[4:5]
	v_lshl_add_u64 v[6:7], v[2:3], 0, v[6:7]
	global_load_dwordx4 v[106:109], v[6:7], off
	global_load_dwordx4 v[206:209], v[6:7], off offset:256
	global_load_dwordx4 v[110:113], v[0:1], off offset:16
	global_load_dwordx4 v[114:117], v[0:1], off
	s_waitcnt lgkmcnt(0)
	v_pk_mul_f32 v[104:105], v[104:105], v[64:65] op_sel_hi:[1,0]
	v_pk_mul_f32 v[100:101], v[100:101], v[64:65] op_sel_hi:[1,0]
	v_pk_mul_f32 v[102:103], v[102:103], v[64:65] op_sel_hi:[1,0]
	v_pk_mul_f32 v[98:99], v[98:99], v[64:65] op_sel_hi:[1,0]
	v_pk_mul_f32 v[94:95], v[94:95], v[64:65] op_sel_hi:[1,0]
	v_pk_mul_f32 v[92:93], v[92:93], v[64:65] op_sel_hi:[1,0]
	v_pk_mul_f32 v[90:91], v[90:91], v[64:65] op_sel_hi:[1,0]
	v_pk_mul_f32 v[96:97], v[96:97], v[64:65] op_sel_hi:[1,0]
	s_waitcnt vmcnt(2)
	v_lshlrev_b32_e32 v118, 16, v106
	v_and_b32_e32 v119, 0xffff0000, v106
	s_waitcnt vmcnt(0)
	v_pk_fma_f32 v[114:115], v[104:105], v[114:115], v[118:119]
	v_lshlrev_b32_e32 v104, 16, v107
	v_and_b32_e32 v105, 0xffff0000, v107
	v_pk_fma_f32 v[116:117], v[100:101], v[116:117], v[104:105]
	v_lshlrev_b32_e32 v100, 16, v108
	v_and_b32_e32 v101, 0xffff0000, v108
	v_pk_fma_f32 v[110:111], v[102:103], v[110:111], v[100:101]
	v_lshlrev_b32_e32 v100, 16, v109
	v_and_b32_e32 v101, 0xffff0000, v109
	v_pk_fma_f32 v[112:113], v[98:99], v[112:113], v[100:101]
	v_cvt_pk_bf16_f32 v106, v114, v115
	v_cvt_pk_bf16_f32 v107, v116, v117
	v_cvt_pk_bf16_f32 v108, v110, v111
	v_cvt_pk_bf16_f32 v109, v112, v113
	global_store_dwordx4 v[6:7], v[106:109], off
	v_pk_mul_f32 v[98:99], v[114:115], v[114:115]
	v_pk_mul_f32 v[100:101], v[116:117], v[116:117]
	v_pk_mul_f32 v[102:103], v[110:111], v[110:111]
	v_pk_mul_f32 v[104:105], v[112:113], v[112:113]
	global_load_dwordx4 v[110:113], v[0:1], off offset:528
	global_load_dwordx4 v[114:117], v[0:1], off offset:512
	v_add_f32_e32 v64, v104, v105
	v_add_f32_e32 v102, v102, v103
	v_add_f32_e32 v100, v100, v101
	v_add_f32_e32 v98, v98, v99
	v_add_f32_e32 v64, v102, v64
	v_add_f32_e32 v98, v98, v100
	v_add_f32_e32 v64, v98, v64
	s_waitcnt vmcnt(2)
; DI unsigned pk2(float lo, float hi) { f32x2_t v = {lo, hi}; bf16x2_t b = __builtin_convertvector(v, bf16x2_t); return __builtin_bit_cast(unsigned, b); }
; DI float bflo(unsigned u) { return __uint_as_float(u << 16); }
; DI float bfhi(unsigned u) { return __uint_as_float(u & 0xffff0000u); }
;     DI void operator()(pg8::f32x4 (&acc)[2][2][4][2], const pg8::Unit& u, int wr, int wc, int fr, int fq) const {
;     ...
;         const int colb = u.pn * 256 + wc * 32 + 8 * fq;
; #pragma unroll
;         for (int ai = 0; ai < 2; ++ai)
; #pragma unroll
;             for (int m = 0; m < 4; ++m) {
;                 const int rl = ai * 128 + wr * 64 + m * 16 + fr; const float r1 = S[rl];
;                 const size_t ro = (size_t)(u.pm * 256 + rl) * 1024 + colb;
;                 float q = 0.f;
; #pragma unroll
;                 for (int bj = 0; bj < 2; ++bj) {
;                     const v4u xw = *(const v4u*)(XB + ro + bj * 128);
;                     const v4f g0 = *(const v4f*)(gpost + colb + bj * 128), g1 = *(const v4f*)(gpost + colb + bj * 128 + 4);
;                     const pg8::f32x4 a0 = acc[ai][bj][m][0], a1 = acc[ai][bj][m][1];
;                     float v[8];
;                     v[0] = bflo(xw.x) + a0[0] * r1 * g0[0]; v[1] = bfhi(xw.x) + a0[1] * r1 * g0[1]; v[2] = bflo(xw.y) + a0[2] * r1 * g0[2]; v[3] = bfhi(xw.y) + a0[3] * r1 * g0[3];
;                     v[4] = bflo(xw.z) + a1[0] * r1 * g1[0]; v[5] = bfhi(xw.z) + a1[1] * r1 * g1[1]; v[6] = bflo(xw.w) + a1[2] * r1 * g1[2]; v[7] = bfhi(xw.w) + a1[3] * r1 * g1[3];
;                     q += ((v[0] * v[0] + v[1] * v[1]) + (v[2] * v[2] + v[3] * v[3])) + ((v[4] * v[4] + v[5] * v[5]) + (v[6] * v[6] + v[7] * v[7]));
;                     if (last) { *(v4f*)(OUT + ro + bj * 128) = (v4f){v[0], v[1], v[2], v[3]}; *(v4f*)(OUT + ro + bj * 128 + 4) = (v4f){v[4], v[5], v[6], v[7]}; }
;                     else { v4u w; w.x = pk2(v[0], v[1]); w.y = pk2(v[2], v[3]); w.z = pk2(v[4], v[5]); w.w = pk2(v[6], v[7]); *(v4u*)(XB + ro + bj * 128) = w; }
;                 }
;                 q += __shfl_xor(q, 16); q += __shfl_xor(q, 32);
;                 if (fq == 0) slots2[(size_t)(u.pm * 256 + rl) * 16 + u.pn * 4 + wc] = q;
;                 if (m & 1) asm volatile("" ::: "memory");
;             }
	v_lshlrev_b32_e32 v118, 16, v206
	v_and_b32_e32 v119, 0xffff0000, v206
	v_lshlrev_b32_e32 v106, 16, v207
	v_and_b32_e32 v107, 0xffff0000, v207
	s_waitcnt vmcnt(0)
	v_pk_fma_f32 v[94:95], v[94:95], v[116:117], v[106:107]
	v_lshlrev_b32_e32 v106, 16, v208
	v_and_b32_e32 v107, 0xffff0000, v208
	v_pk_fma_f32 v[92:93], v[92:93], v[110:111], v[106:107]
	v_lshlrev_b32_e32 v106, 16, v209
	v_and_b32_e32 v107, 0xffff0000, v209
	v_pk_fma_f32 v[106:107], v[90:91], v[112:113], v[106:107]
	v_pk_fma_f32 v[96:97], v[96:97], v[114:115], v[118:119]
	v_pk_mul_f32 v[110:111], v[92:93], v[92:93]
	v_pk_mul_f32 v[112:113], v[106:107], v[106:107]
	v_pk_mul_f32 v[90:91], v[96:97], v[96:97]
	v_pk_mul_f32 v[108:109], v[94:95], v[94:95]
	v_add_f32_e32 v98, v112, v113
	v_add_f32_e32 v99, v110, v111
	v_add_f32_e32 v98, v99, v98
	v_add_f32_e32 v99, v108, v109
	v_add_f32_e32 v90, v90, v91
	v_add_f32_e32 v90, v90, v99
	v_add_f32_e32 v90, v90, v98
	v_add_f32_e32 v64, v64, v90
	v_cvt_pk_bf16_f32 v90, v96, v97
	v_cvt_pk_bf16_f32 v91, v94, v95
	v_cvt_pk_bf16_f32 v92, v92, v93
	v_cvt_pk_bf16_f32 v93, v106, v107
	global_store_dwordx4 v[6:7], v[90:93], off offset:256
	ds_bpermute_b32 v6, v177, v64
	s_waitcnt lgkmcnt(0)
	v_add_f32_e32 v6, v64, v6
	ds_bpermute_b32 v7, v178, v6
	s_and_saveexec_b64 s[22:23], s[38:39]
	s_cbranch_execz .LBB0_432
	v_lshlrev_b64 v[4:5], 6, v[4:5]
	v_lshl_add_u64 v[4:5], s[20:21], 0, v[4:5]
	s_waitcnt lgkmcnt(0)
	v_add_f32_e32 v6, v6, v7
	global_store_dword v[4:5], v6, off
.LBB0_432:
	s_or_b64 exec, exec, s[22:23]
	v_lshl_add_u32 v4, v166, 2, s68
	global_load_dwordx4 v[90:93], v[0:1], off offset:16
	global_load_dwordx4 v[94:97], v[0:1], off
	ds_read_b32 v64, v4
	v_add_u32_e32 v4, v150, v166
	v_ashrrev_i32_e32 v5, 31, v4
	s_waitcnt lgkmcnt(1)
	v_lshlrev_b64 v[6:7], 11, v[4:5]
	v_lshl_add_u64 v[6:7], v[2:3], 0, v[6:7]
	global_load_dwordx4 v[98:101], v[6:7], off
	global_load_dwordx4 v[206:209], v[6:7], off offset:256
	s_waitcnt lgkmcnt(0)
	v_pk_mul_f32 v[88:89], v[88:89], v[64:65] op_sel_hi:[1,0]
	v_pk_mul_f32 v[84:85], v[84:85], v[64:65] op_sel_hi:[1,0]
	v_pk_mul_f32 v[86:87], v[86:87], v[64:65] op_sel_hi:[1,0]
	v_pk_mul_f32 v[82:83], v[82:83], v[64:65] op_sel_hi:[1,0]
	v_pk_mul_f32 v[78:79], v[78:79], v[64:65] op_sel_hi:[1,0]
	v_pk_mul_f32 v[76:77], v[76:77], v[64:65] op_sel_hi:[1,0]
	v_pk_mul_f32 v[74:75], v[74:75], v[64:65] op_sel_hi:[1,0]
	v_pk_mul_f32 v[80:81], v[80:81], v[64:65] op_sel_hi:[1,0]
	s_waitcnt vmcnt(0)
	v_lshlrev_b32_e32 v102, 16, v98
	v_and_b32_e32 v103, 0xffff0000, v98
	v_pk_fma_f32 v[94:95], v[94:95], v[88:89], v[102:103]
	v_lshlrev_b32_e32 v88, 16, v99
	v_and_b32_e32 v89, 0xffff0000, v99
	v_pk_fma_f32 v[96:97], v[96:97], v[84:85], v[88:89]
	v_lshlrev_b32_e32 v84, 16, v100
	v_and_b32_e32 v85, 0xffff0000, v100
	v_pk_fma_f32 v[98:99], v[90:91], v[86:87], v[84:85]
	v_lshlrev_b32_e32 v84, 16, v101
	v_and_b32_e32 v85, 0xffff0000, v101
	v_pk_fma_f32 v[100:101], v[92:93], v[82:83], v[84:85]
	v_cvt_pk_bf16_f32 v90, v94, v95
	v_cvt_pk_bf16_f32 v91, v96, v97
	v_cvt_pk_bf16_f32 v92, v98, v99
	v_cvt_pk_bf16_f32 v93, v100, v101
	global_store_dwordx4 v[6:7], v[90:93], off
	v_pk_mul_f32 v[82:83], v[94:95], v[94:95]
	v_pk_mul_f32 v[84:85], v[96:97], v[96:97]
	v_pk_mul_f32 v[86:87], v[98:99], v[98:99]
	v_pk_mul_f32 v[88:89], v[100:101], v[100:101]
	global_load_dwordx4 v[94:97], v[0:1], off offset:528
	global_load_dwordx4 v[98:101], v[0:1], off offset:512
	v_add_f32_e32 v64, v88, v89
	v_add_f32_e32 v86, v86, v87
	v_add_f32_e32 v84, v84, v85
	v_add_f32_e32 v82, v82, v83
	v_add_f32_e32 v64, v86, v64
	v_add_f32_e32 v82, v82, v84
	v_add_f32_e32 v64, v82, v64
	s_waitcnt vmcnt(2)
	v_lshlrev_b32_e32 v102, 16, v206
	v_and_b32_e32 v103, 0xffff0000, v206
	v_lshlrev_b32_e32 v90, 16, v207
	v_and_b32_e32 v91, 0xffff0000, v207
	s_waitcnt vmcnt(0)
	v_pk_fma_f32 v[78:79], v[78:79], v[100:101], v[90:91]
	v_lshlrev_b32_e32 v90, 16, v208
	v_and_b32_e32 v91, 0xffff0000, v208
	v_pk_fma_f32 v[76:77], v[76:77], v[94:95], v[90:91]
	v_lshlrev_b32_e32 v90, 16, v209
	v_and_b32_e32 v91, 0xffff0000, v209
	v_pk_fma_f32 v[90:91], v[74:75], v[96:97], v[90:91]
	v_pk_fma_f32 v[80:81], v[80:81], v[98:99], v[102:103]
	v_pk_mul_f32 v[94:95], v[76:77], v[76:77]
	v_pk_mul_f32 v[96:97], v[90:91], v[90:91]
	v_pk_mul_f32 v[74:75], v[80:81], v[80:81]
	v_pk_mul_f32 v[92:93], v[78:79], v[78:79]
	v_add_f32_e32 v82, v96, v97
	v_add_f32_e32 v83, v94, v95
	v_add_f32_e32 v82, v83, v82
	v_add_f32_e32 v83, v92, v93
	v_add_f32_e32 v74, v74, v75
	v_add_f32_e32 v74, v74, v83
	v_add_f32_e32 v74, v74, v82
	v_add_f32_e32 v64, v64, v74
	v_cvt_pk_bf16_f32 v74, v80, v81
	v_cvt_pk_bf16_f32 v75, v78, v79
	v_cvt_pk_bf16_f32 v76, v76, v77
	v_cvt_pk_bf16_f32 v77, v90, v91
	global_store_dwordx4 v[6:7], v[74:77], off offset:256
	ds_bpermute_b32 v6, v177, v64
	s_waitcnt lgkmcnt(0)
	v_add_f32_e32 v6, v64, v6
	ds_bpermute_b32 v7, v178, v6
	s_and_saveexec_b64 s[22:23], s[38:39]
	s_cbranch_execz .LBB0_434
	v_lshlrev_b64 v[4:5], 6, v[4:5]
	v_lshl_add_u64 v[4:5], s[20:21], 0, v[4:5]
	s_waitcnt lgkmcnt(0)
	v_add_f32_e32 v6, v6, v7
	global_store_dword v[4:5], v6, off
; DI unsigned pk2(float lo, float hi) { f32x2_t v = {lo, hi}; bf16x2_t b = __builtin_convertvector(v, bf16x2_t); return __builtin_bit_cast(unsigned, b); }
; DI float bflo(unsigned u) { return __uint_as_float(u << 16); }
; DI float bfhi(unsigned u) { return __uint_as_float(u & 0xffff0000u); }
;     DI void operator()(pg8::f32x4 (&acc)[2][2][4][2], const pg8::Unit& u, int wr, int wc, int fr, int fq) const {
;     ...
;         const int colb = u.pn * 256 + wc * 32 + 8 * fq;
; #pragma unroll
;         for (int ai = 0; ai < 2; ++ai)
; #pragma unroll
;             for (int m = 0; m < 4; ++m) {
;                 const int rl = ai * 128 + wr * 64 + m * 16 + fr; const float r1 = S[rl];
;                 const size_t ro = (size_t)(u.pm * 256 + rl) * 1024 + colb;
;                 float q = 0.f;
; #pragma unroll
;                 for (int bj = 0; bj < 2; ++bj) {
;                     const v4u xw = *(const v4u*)(XB + ro + bj * 128);
;                     const v4f g0 = *(const v4f*)(gpost + colb + bj * 128), g1 = *(const v4f*)(gpost + colb + bj * 128 + 4);
;                     const pg8::f32x4 a0 = acc[ai][bj][m][0], a1 = acc[ai][bj][m][1];
;                     float v[8];
;                     v[0] = bflo(xw.x) + a0[0] * r1 * g0[0]; v[1] = bfhi(xw.x) + a0[1] * r1 * g0[1]; v[2] = bflo(xw.y) + a0[2] * r1 * g0[2]; v[3] = bfhi(xw.y) + a0[3] * r1 * g0[3];
;                     v[4] = bflo(xw.z) + a1[0] * r1 * g1[0]; v[5] = bfhi(xw.z) + a1[1] * r1 * g1[1]; v[6] = bflo(xw.w) + a1[2] * r1 * g1[2]; v[7] = bfhi(xw.w) + a1[3] * r1 * g1[3];
;                     q += ((v[0] * v[0] + v[1] * v[1]) + (v[2] * v[2] + v[3] * v[3])) + ((v[4] * v[4] + v[5] * v[5]) + (v[6] * v[6] + v[7] * v[7]));
;                     if (last) { *(v4f*)(OUT + ro + bj * 128) = (v4f){v[0], v[1], v[2], v[3]}; *(v4f*)(OUT + ro + bj * 128 + 4) = (v4f){v[4], v[5], v[6], v[7]}; }
;                     else { v4u w; w.x = pk2(v[0], v[1]); w.y = pk2(v[2], v[3]); w.z = pk2(v[4], v[5]); w.w = pk2(v[6], v[7]); *(v4u*)(XB + ro + bj * 128) = w; }
;                 }
;                 q += __shfl_xor(q, 16); q += __shfl_xor(q, 32);
;                 if (fq == 0) slots2[(size_t)(u.pm * 256 + rl) * 16 + u.pn * 4 + wc] = q;
;                 if (m & 1) asm volatile("" ::: "memory");
;             }
.LBB0_434:
	s_or_b64 exec, exec, s[22:23]
	v_lshl_add_u32 v4, v167, 2, s68
	ds_read_b32 v64, v4
	v_add_u32_e32 v4, v150, v167
	v_ashrrev_i32_e32 v5, 31, v4
	s_waitcnt lgkmcnt(1)
	v_lshlrev_b64 v[6:7], 11, v[4:5]
	v_lshl_add_u64 v[6:7], v[2:3], 0, v[6:7]
	global_load_dwordx4 v[74:77], v[6:7], off
	global_load_dwordx4 v[206:209], v[6:7], off offset:256
	global_load_dwordx4 v[78:81], v[0:1], off offset:16
	global_load_dwordx4 v[82:85], v[0:1], off
	s_waitcnt lgkmcnt(0)
	v_pk_mul_f32 v[72:73], v[72:73], v[64:65] op_sel_hi:[1,0]
	v_pk_mul_f32 v[68:69], v[68:69], v[64:65] op_sel_hi:[1,0]
	v_pk_mul_f32 v[70:71], v[70:71], v[64:65] op_sel_hi:[1,0]
	v_pk_mul_f32 v[66:67], v[66:67], v[64:65] op_sel_hi:[1,0]
	v_pk_mul_f32 v[60:61], v[60:61], v[64:65] op_sel_hi:[1,0]
	v_pk_mul_f32 v[58:59], v[58:59], v[64:65] op_sel_hi:[1,0]
	v_pk_mul_f32 v[56:57], v[56:57], v[64:65] op_sel_hi:[1,0]
	v_pk_mul_f32 v[62:63], v[62:63], v[64:65] op_sel_hi:[1,0]
	s_waitcnt vmcnt(2)
	v_lshlrev_b32_e32 v86, 16, v74
	v_and_b32_e32 v87, 0xffff0000, v74
	s_waitcnt vmcnt(0)
	v_pk_fma_f32 v[82:83], v[72:73], v[82:83], v[86:87]
	v_lshlrev_b32_e32 v72, 16, v75
	v_and_b32_e32 v73, 0xffff0000, v75
	v_pk_fma_f32 v[84:85], v[68:69], v[84:85], v[72:73]
	v_lshlrev_b32_e32 v68, 16, v76
	v_and_b32_e32 v69, 0xffff0000, v76
	v_pk_fma_f32 v[78:79], v[70:71], v[78:79], v[68:69]
	v_lshlrev_b32_e32 v68, 16, v77
	v_and_b32_e32 v69, 0xffff0000, v77
	v_pk_fma_f32 v[80:81], v[66:67], v[80:81], v[68:69]
	v_cvt_pk_bf16_f32 v74, v82, v83
	v_cvt_pk_bf16_f32 v75, v84, v85
	v_cvt_pk_bf16_f32 v76, v78, v79
	v_cvt_pk_bf16_f32 v77, v80, v81
	global_store_dwordx4 v[6:7], v[74:77], off
	v_pk_mul_f32 v[66:67], v[82:83], v[82:83]
	v_pk_mul_f32 v[68:69], v[84:85], v[84:85]
	v_pk_mul_f32 v[70:71], v[78:79], v[78:79]
	v_pk_mul_f32 v[72:73], v[80:81], v[80:81]
	global_load_dwordx4 v[78:81], v[0:1], off offset:528
	global_load_dwordx4 v[82:85], v[0:1], off offset:512
	v_add_f32_e32 v64, v72, v73
	v_add_f32_e32 v70, v70, v71
	v_add_f32_e32 v68, v68, v69
	v_add_f32_e32 v66, v66, v67
	v_add_f32_e32 v64, v70, v64
	v_add_f32_e32 v66, v66, v68
	v_add_f32_e32 v64, v66, v64
	s_waitcnt vmcnt(2)
	v_lshlrev_b32_e32 v86, 16, v206
	v_and_b32_e32 v87, 0xffff0000, v206
	v_lshlrev_b32_e32 v74, 16, v207
	v_and_b32_e32 v75, 0xffff0000, v207
	s_waitcnt vmcnt(0)
	v_pk_fma_f32 v[60:61], v[60:61], v[84:85], v[74:75]
	v_lshlrev_b32_e32 v74, 16, v208
	v_and_b32_e32 v75, 0xffff0000, v208
	v_pk_fma_f32 v[58:59], v[58:59], v[78:79], v[74:75]
	v_lshlrev_b32_e32 v74, 16, v209
	v_and_b32_e32 v75, 0xffff0000, v209
	v_pk_fma_f32 v[74:75], v[56:57], v[80:81], v[74:75]
	v_pk_fma_f32 v[62:63], v[62:63], v[82:83], v[86:87]
	v_pk_mul_f32 v[78:79], v[58:59], v[58:59]
	v_pk_mul_f32 v[80:81], v[74:75], v[74:75]
	v_pk_mul_f32 v[56:57], v[62:63], v[62:63]
	v_pk_mul_f32 v[76:77], v[60:61], v[60:61]
	v_add_f32_e32 v66, v80, v81
	v_add_f32_e32 v67, v78, v79
	v_add_f32_e32 v66, v67, v66
	v_add_f32_e32 v67, v76, v77
	v_add_f32_e32 v56, v56, v57
	v_add_f32_e32 v56, v56, v67
	v_add_f32_e32 v56, v56, v66
	v_add_f32_e32 v64, v64, v56
	v_cvt_pk_bf16_f32 v56, v62, v63
	v_cvt_pk_bf16_f32 v57, v60, v61
	v_cvt_pk_bf16_f32 v58, v58, v59
	v_cvt_pk_bf16_f32 v59, v74, v75
	global_store_dwordx4 v[6:7], v[56:59], off offset:256
	ds_bpermute_b32 v6, v177, v64
	s_waitcnt lgkmcnt(0)
	v_add_f32_e32 v6, v64, v6
	ds_bpermute_b32 v7, v178, v6
	s_and_saveexec_b64 s[22:23], s[38:39]
	s_cbranch_execz .LBB0_436
	v_lshlrev_b64 v[4:5], 6, v[4:5]
	v_lshl_add_u64 v[4:5], s[20:21], 0, v[4:5]
	s_waitcnt lgkmcnt(0)
	v_add_f32_e32 v6, v6, v7
	global_store_dword v[4:5], v6, off
.LBB0_436:
	s_or_b64 exec, exec, s[22:23]
	v_lshl_add_u32 v4, v168, 2, s68
	global_load_dwordx4 v[58:61], v[0:1], off offset:16
	global_load_dwordx4 v[66:69], v[0:1], off
	ds_read_b32 v56, v4
	v_add_u32_e32 v4, v150, v168
	v_ashrrev_i32_e32 v5, 31, v4
	s_waitcnt lgkmcnt(1)
	v_lshlrev_b64 v[6:7], 11, v[4:5]
	v_lshl_add_u64 v[6:7], v[2:3], 0, v[6:7]
	global_load_dwordx4 v[70:73], v[6:7], off
	global_load_dwordx4 v[206:209], v[6:7], off offset:256
	s_waitcnt lgkmcnt(0)
	v_pk_mul_f32 v[54:55], v[54:55], v[56:57] op_sel_hi:[1,0]
	v_pk_mul_f32 v[50:51], v[50:51], v[56:57] op_sel_hi:[1,0]
	v_pk_mul_f32 v[52:53], v[52:53], v[56:57] op_sel_hi:[1,0]
	v_pk_mul_f32 v[48:49], v[48:49], v[56:57] op_sel_hi:[1,0]
	v_pk_mul_f32 v[44:45], v[44:45], v[56:57] op_sel_hi:[1,0]
	v_pk_mul_f32 v[42:43], v[42:43], v[56:57] op_sel_hi:[1,0]
	v_pk_mul_f32 v[40:41], v[40:41], v[56:57] op_sel_hi:[1,0]
	v_pk_mul_f32 v[46:47], v[46:47], v[56:57] op_sel_hi:[1,0]
	s_waitcnt vmcnt(0)
	v_lshlrev_b32_e32 v62, 16, v70
	v_and_b32_e32 v63, 0xffff0000, v70
	v_pk_fma_f32 v[62:63], v[66:67], v[54:55], v[62:63]
	v_lshlrev_b32_e32 v54, 16, v71
	v_and_b32_e32 v55, 0xffff0000, v71
	v_pk_fma_f32 v[66:67], v[68:69], v[50:51], v[54:55]
	v_lshlrev_b32_e32 v50, 16, v72
	v_and_b32_e32 v51, 0xffff0000, v72
	v_pk_fma_f32 v[68:69], v[58:59], v[52:53], v[50:51]
	v_lshlrev_b32_e32 v50, 16, v73
	v_and_b32_e32 v51, 0xffff0000, v73
	v_pk_fma_f32 v[70:71], v[60:61], v[48:49], v[50:51]
	v_cvt_pk_bf16_f32 v58, v62, v63
	v_cvt_pk_bf16_f32 v59, v66, v67
	v_cvt_pk_bf16_f32 v60, v68, v69
	v_cvt_pk_bf16_f32 v61, v70, v71
	global_store_dwordx4 v[6:7], v[58:61], off
	v_pk_mul_f32 v[50:51], v[66:67], v[66:67]
	v_pk_mul_f32 v[52:53], v[68:69], v[68:69]
	v_pk_mul_f32 v[54:55], v[70:71], v[70:71]
	global_load_dwordx4 v[66:69], v[0:1], off offset:528
	global_load_dwordx4 v[70:73], v[0:1], off offset:512
	v_pk_mul_f32 v[48:49], v[62:63], v[62:63]
	v_add_f32_e32 v50, v50, v51
	v_add_f32_e32 v48, v48, v49
	v_add_f32_e32 v48, v48, v50
	v_add_f32_e32 v54, v54, v55
	v_add_f32_e32 v52, v52, v53
	v_add_f32_e32 v52, v52, v54
	v_add_f32_e32 v48, v48, v52
	s_waitcnt vmcnt(2)
	v_lshlrev_b32_e32 v62, 16, v206
	v_and_b32_e32 v63, 0xffff0000, v206
	v_lshlrev_b32_e32 v58, 16, v207
	v_and_b32_e32 v59, 0xffff0000, v207
	s_waitcnt vmcnt(0)
	v_pk_fma_f32 v[44:45], v[44:45], v[72:73], v[58:59]
	v_lshlrev_b32_e32 v58, 16, v208
	v_and_b32_e32 v59, 0xffff0000, v208
	v_pk_fma_f32 v[42:43], v[42:43], v[66:67], v[58:59]
	v_lshlrev_b32_e32 v58, 16, v209
	v_and_b32_e32 v59, 0xffff0000, v209
	v_pk_fma_f32 v[56:57], v[40:41], v[68:69], v[58:59]
	v_pk_fma_f32 v[46:47], v[46:47], v[70:71], v[62:63]
	v_pk_mul_f32 v[60:61], v[42:43], v[42:43]
	v_pk_mul_f32 v[62:63], v[56:57], v[56:57]
	v_pk_mul_f32 v[40:41], v[46:47], v[46:47]
	v_pk_mul_f32 v[58:59], v[44:45], v[44:45]
	v_add_f32_e32 v49, v62, v63
	v_add_f32_e32 v50, v60, v61
	v_add_f32_e32 v49, v50, v49
	v_add_f32_e32 v50, v58, v59
	v_add_f32_e32 v40, v40, v41
	v_add_f32_e32 v40, v40, v50
	v_add_f32_e32 v40, v40, v49
	v_add_f32_e32 v48, v48, v40
	v_cvt_pk_bf16_f32 v40, v46, v47
	v_cvt_pk_bf16_f32 v41, v44, v45
	v_cvt_pk_bf16_f32 v42, v42, v43
	v_cvt_pk_bf16_f32 v43, v56, v57
	global_store_dwordx4 v[6:7], v[40:43], off offset:256
	ds_bpermute_b32 v6, v177, v48
	s_waitcnt lgkmcnt(0)
	v_add_f32_e32 v6, v48, v6
	ds_bpermute_b32 v7, v178, v6
	s_and_saveexec_b64 s[22:23], s[38:39]
	s_cbranch_execz .LBB0_438
; DI unsigned pk2(float lo, float hi) { f32x2_t v = {lo, hi}; bf16x2_t b = __builtin_convertvector(v, bf16x2_t); return __builtin_bit_cast(unsigned, b); }
; DI float bflo(unsigned u) { return __uint_as_float(u << 16); }
; DI float bfhi(unsigned u) { return __uint_as_float(u & 0xffff0000u); }
;     DI void operator()(pg8::f32x4 (&acc)[2][2][4][2], const pg8::Unit& u, int wr, int wc, int fr, int fq) const {
;     ...
;         const int colb = u.pn * 256 + wc * 32 + 8 * fq;
; #pragma unroll
;         for (int ai = 0; ai < 2; ++ai)
; #pragma unroll
;             for (int m = 0; m < 4; ++m) {
;                 const int rl = ai * 128 + wr * 64 + m * 16 + fr; const float r1 = S[rl];
;                 const size_t ro = (size_t)(u.pm * 256 + rl) * 1024 + colb;
;                 float q = 0.f;
; #pragma unroll
;                 for (int bj = 0; bj < 2; ++bj) {
;                     const v4u xw = *(const v4u*)(XB + ro + bj * 128);
;                     const v4f g0 = *(const v4f*)(gpost + colb + bj * 128), g1 = *(const v4f*)(gpost + colb + bj * 128 + 4);
;                     const pg8::f32x4 a0 = acc[ai][bj][m][0], a1 = acc[ai][bj][m][1];
;                     float v[8];
;                     v[0] = bflo(xw.x) + a0[0] * r1 * g0[0]; v[1] = bfhi(xw.x) + a0[1] * r1 * g0[1]; v[2] = bflo(xw.y) + a0[2] * r1 * g0[2]; v[3] = bfhi(xw.y) + a0[3] * r1 * g0[3];
;                     v[4] = bflo(xw.z) + a1[0] * r1 * g1[0]; v[5] = bfhi(xw.z) + a1[1] * r1 * g1[1]; v[6] = bflo(xw.w) + a1[2] * r1 * g1[2]; v[7] = bfhi(xw.w) + a1[3] * r1 * g1[3];
;                     q += ((v[0] * v[0] + v[1] * v[1]) + (v[2] * v[2] + v[3] * v[3])) + ((v[4] * v[4] + v[5] * v[5]) + (v[6] * v[6] + v[7] * v[7]));
;                     if (last) { *(v4f*)(OUT + ro + bj * 128) = (v4f){v[0], v[1], v[2], v[3]}; *(v4f*)(OUT + ro + bj * 128 + 4) = (v4f){v[4], v[5], v[6], v[7]}; }
;                     else { v4u w; w.x = pk2(v[0], v[1]); w.y = pk2(v[2], v[3]); w.z = pk2(v[4], v[5]); w.w = pk2(v[6], v[7]); *(v4u*)(XB + ro + bj * 128) = w; }
;                 }
;                 q += __shfl_xor(q, 16); q += __shfl_xor(q, 32);
;                 if (fq == 0) slots2[(size_t)(u.pm * 256 + rl) * 16 + u.pn * 4 + wc] = q;
;                 if (m & 1) asm volatile("" ::: "memory");
;             }
	v_lshlrev_b64 v[4:5], 6, v[4:5]
	v_lshl_add_u64 v[4:5], s[20:21], 0, v[4:5]
	s_waitcnt lgkmcnt(0)
	v_add_f32_e32 v6, v6, v7
	global_store_dword v[4:5], v6, off
.LBB0_438:
	s_or_b64 exec, exec, s[22:23]
	v_lshl_add_u32 v4, v169, 2, s68
	ds_read_b32 v40, v4
	v_add_u32_e32 v4, v150, v169
	v_ashrrev_i32_e32 v5, 31, v4
	s_waitcnt lgkmcnt(1)
	v_lshlrev_b64 v[6:7], 11, v[4:5]
	v_lshl_add_u64 v[6:7], v[2:3], 0, v[6:7]
	global_load_dwordx4 v[42:45], v[6:7], off
	global_load_dwordx4 v[206:209], v[6:7], off offset:256
	global_load_dwordx4 v[46:49], v[0:1], off offset:16
	global_load_dwordx4 v[50:53], v[0:1], off
	s_waitcnt lgkmcnt(0)
	v_pk_mul_f32 v[38:39], v[38:39], v[40:41] op_sel_hi:[1,0]
	v_pk_mul_f32 v[34:35], v[34:35], v[40:41] op_sel_hi:[1,0]
	v_pk_mul_f32 v[36:37], v[36:37], v[40:41] op_sel_hi:[1,0]
	v_pk_mul_f32 v[32:33], v[32:33], v[40:41] op_sel_hi:[1,0]
	v_pk_mul_f32 v[28:29], v[28:29], v[40:41] op_sel_hi:[1,0]
	v_pk_mul_f32 v[26:27], v[26:27], v[40:41] op_sel_hi:[1,0]
	v_pk_mul_f32 v[24:25], v[24:25], v[40:41] op_sel_hi:[1,0]
	v_pk_mul_f32 v[30:31], v[30:31], v[40:41] op_sel_hi:[1,0]
	s_waitcnt vmcnt(2)
	v_lshlrev_b32_e32 v54, 16, v42
	v_and_b32_e32 v55, 0xffff0000, v42
	s_waitcnt vmcnt(0)
	v_pk_fma_f32 v[50:51], v[38:39], v[50:51], v[54:55]
	v_lshlrev_b32_e32 v38, 16, v43
	v_and_b32_e32 v39, 0xffff0000, v43
	v_pk_fma_f32 v[52:53], v[34:35], v[52:53], v[38:39]
	v_lshlrev_b32_e32 v34, 16, v44
	v_and_b32_e32 v35, 0xffff0000, v44
	v_pk_fma_f32 v[46:47], v[36:37], v[46:47], v[34:35]
	v_lshlrev_b32_e32 v34, 16, v45
	v_and_b32_e32 v35, 0xffff0000, v45
	v_pk_fma_f32 v[48:49], v[32:33], v[48:49], v[34:35]
	v_cvt_pk_bf16_f32 v42, v50, v51
	v_cvt_pk_bf16_f32 v43, v52, v53
	v_cvt_pk_bf16_f32 v44, v46, v47
	v_cvt_pk_bf16_f32 v45, v48, v49
	global_store_dwordx4 v[6:7], v[42:45], off
	v_pk_mul_f32 v[32:33], v[50:51], v[50:51]
	v_pk_mul_f32 v[34:35], v[52:53], v[52:53]
	v_pk_mul_f32 v[36:37], v[46:47], v[46:47]
	v_pk_mul_f32 v[38:39], v[48:49], v[48:49]
	global_load_dwordx4 v[46:49], v[0:1], off offset:528
	global_load_dwordx4 v[50:53], v[0:1], off offset:512
	v_add_f32_e32 v34, v34, v35
	v_add_f32_e32 v32, v32, v33
	v_add_f32_e32 v32, v32, v34
	v_add_f32_e32 v38, v38, v39
	v_add_f32_e32 v36, v36, v37
	v_add_f32_e32 v36, v36, v38
	v_add_f32_e32 v32, v32, v36
	s_waitcnt vmcnt(2)
	v_lshlrev_b32_e32 v54, 16, v206
	v_and_b32_e32 v55, 0xffff0000, v206
	v_lshlrev_b32_e32 v42, 16, v207
	v_and_b32_e32 v43, 0xffff0000, v207
	s_waitcnt vmcnt(0)
	v_pk_fma_f32 v[28:29], v[28:29], v[52:53], v[42:43]
	v_lshlrev_b32_e32 v42, 16, v208
	v_and_b32_e32 v43, 0xffff0000, v208
	v_pk_fma_f32 v[26:27], v[26:27], v[46:47], v[42:43]
	v_lshlrev_b32_e32 v42, 16, v209
	v_and_b32_e32 v43, 0xffff0000, v209
	v_pk_fma_f32 v[40:41], v[24:25], v[48:49], v[42:43]
	v_pk_fma_f32 v[30:31], v[30:31], v[50:51], v[54:55]
	v_pk_mul_f32 v[44:45], v[26:27], v[26:27]
	v_pk_mul_f32 v[46:47], v[40:41], v[40:41]
	v_pk_mul_f32 v[24:25], v[30:31], v[30:31]
	v_pk_mul_f32 v[42:43], v[28:29], v[28:29]
	v_add_f32_e32 v33, v46, v47
	v_add_f32_e32 v34, v44, v45
	v_add_f32_e32 v33, v34, v33
	v_add_f32_e32 v34, v42, v43
	v_add_f32_e32 v24, v24, v25
	v_add_f32_e32 v24, v24, v34
	v_add_f32_e32 v24, v24, v33
	v_add_f32_e32 v32, v32, v24
	v_cvt_pk_bf16_f32 v24, v30, v31
	v_cvt_pk_bf16_f32 v25, v28, v29
	v_cvt_pk_bf16_f32 v26, v26, v27
	v_cvt_pk_bf16_f32 v27, v40, v41
	global_store_dwordx4 v[6:7], v[24:27], off offset:256
	ds_bpermute_b32 v6, v177, v32
	s_waitcnt lgkmcnt(0)
	v_add_f32_e32 v6, v32, v6
	ds_bpermute_b32 v7, v178, v6
	s_and_saveexec_b64 s[22:23], s[38:39]
	s_cbranch_execz .LBB0_440
	v_lshlrev_b64 v[4:5], 6, v[4:5]
	v_lshl_add_u64 v[4:5], s[20:21], 0, v[4:5]
	s_waitcnt lgkmcnt(0)
	v_add_f32_e32 v6, v6, v7
	global_store_dword v[4:5], v6, off
; DI unsigned pk2(float lo, float hi) { f32x2_t v = {lo, hi}; bf16x2_t b = __builtin_convertvector(v, bf16x2_t); return __builtin_bit_cast(unsigned, b); }
; DI float bflo(unsigned u) { return __uint_as_float(u << 16); }
; DI float bfhi(unsigned u) { return __uint_as_float(u & 0xffff0000u); }
;     DI void operator()(pg8::f32x4 (&acc)[2][2][4][2], const pg8::Unit& u, int wr, int wc, int fr, int fq) const {
;     ...
;         const int colb = u.pn * 256 + wc * 32 + 8 * fq;
; #pragma unroll
;         for (int ai = 0; ai < 2; ++ai)
; #pragma unroll
;             for (int m = 0; m < 4; ++m) {
;                 const int rl = ai * 128 + wr * 64 + m * 16 + fr; const float r1 = S[rl];
;                 const size_t ro = (size_t)(u.pm * 256 + rl) * 1024 + colb;
;                 float q = 0.f;
; #pragma unroll
;                 for (int bj = 0; bj < 2; ++bj) {
;                     const v4u xw = *(const v4u*)(XB + ro + bj * 128);
;                     const v4f g0 = *(const v4f*)(gpost + colb + bj * 128), g1 = *(const v4f*)(gpost + colb + bj * 128 + 4);
;                     const pg8::f32x4 a0 = acc[ai][bj][m][0], a1 = acc[ai][bj][m][1];
;                     float v[8];
;                     v[0] = bflo(xw.x) + a0[0] * r1 * g0[0]; v[1] = bfhi(xw.x) + a0[1] * r1 * g0[1]; v[2] = bflo(xw.y) + a0[2] * r1 * g0[2]; v[3] = bfhi(xw.y) + a0[3] * r1 * g0[3];
;                     v[4] = bflo(xw.z) + a1[0] * r1 * g1[0]; v[5] = bfhi(xw.z) + a1[1] * r1 * g1[1]; v[6] = bflo(xw.w) + a1[2] * r1 * g1[2]; v[7] = bfhi(xw.w) + a1[3] * r1 * g1[3];
;                     q += ((v[0] * v[0] + v[1] * v[1]) + (v[2] * v[2] + v[3] * v[3])) + ((v[4] * v[4] + v[5] * v[5]) + (v[6] * v[6] + v[7] * v[7]));
;                     if (last) { *(v4f*)(OUT + ro + bj * 128) = (v4f){v[0], v[1], v[2], v[3]}; *(v4f*)(OUT + ro + bj * 128 + 4) = (v4f){v[4], v[5], v[6], v[7]}; }
;                     else { v4u w; w.x = pk2(v[0], v[1]); w.y = pk2(v[2], v[3]); w.z = pk2(v[4], v[5]); w.w = pk2(v[6], v[7]); *(v4u*)(XB + ro + bj * 128) = w; }
;                 }
;                 q += __shfl_xor(q, 16); q += __shfl_xor(q, 32);
;                 if (fq == 0) slots2[(size_t)(u.pm * 256 + rl) * 16 + u.pn * 4 + wc] = q;
;                 if (m & 1) asm volatile("" ::: "memory");
;             }
.LBB0_440:
	s_or_b64 exec, exec, s[22:23]
	v_lshl_add_u32 v4, v170, 2, s68
	global_load_dwordx4 v[26:29], v[0:1], off offset:16
	global_load_dwordx4 v[30:33], v[0:1], off
	ds_read_b32 v24, v4
	v_add_u32_e32 v4, v150, v170
	v_ashrrev_i32_e32 v5, 31, v4
	s_waitcnt lgkmcnt(1)
	v_lshlrev_b64 v[6:7], 11, v[4:5]
	v_lshl_add_u64 v[2:3], v[2:3], 0, v[6:7]
	global_load_dwordx4 v[34:37], v[2:3], off
	global_load_dwordx4 v[206:209], v[2:3], off offset:256
	s_waitcnt lgkmcnt(0)
	v_pk_mul_f32 v[22:23], v[22:23], v[24:25] op_sel_hi:[1,0]
	v_pk_mul_f32 v[18:19], v[18:19], v[24:25] op_sel_hi:[1,0]
	v_pk_mul_f32 v[16:17], v[16:17], v[24:25] op_sel_hi:[1,0]
	v_pk_mul_f32 v[14:15], v[14:15], v[24:25] op_sel_hi:[1,0]
	v_pk_mul_f32 v[12:13], v[12:13], v[24:25] op_sel_hi:[1,0]
	v_pk_mul_f32 v[10:11], v[10:11], v[24:25] op_sel_hi:[1,0]
	v_pk_mul_f32 v[8:9], v[8:9], v[24:25] op_sel_hi:[1,0]
	s_waitcnt vmcnt(0)
	v_lshlrev_b32_e32 v6, 16, v34
	v_and_b32_e32 v7, 0xffff0000, v34
	v_pk_fma_f32 v[22:23], v[30:31], v[22:23], v[6:7]
	v_lshlrev_b32_e32 v6, 16, v35
	v_and_b32_e32 v7, 0xffff0000, v35
	v_pk_fma_f32 v[30:31], v[32:33], v[18:19], v[6:7]
	v_lshlrev_b32_e32 v6, 16, v36
	v_and_b32_e32 v7, 0xffff0000, v36
	v_pk_mul_f32 v[18:19], v[20:21], v[24:25] op_sel_hi:[1,0]
	s_nop 0
	v_pk_fma_f32 v[32:33], v[26:27], v[18:19], v[6:7]
	v_lshlrev_b32_e32 v6, 16, v37
	v_and_b32_e32 v7, 0xffff0000, v37
	v_pk_fma_f32 v[34:35], v[28:29], v[16:17], v[6:7]
	v_cvt_pk_bf16_f32 v26, v22, v23
	v_cvt_pk_bf16_f32 v27, v30, v31
	v_cvt_pk_bf16_f32 v28, v32, v33
	v_cvt_pk_bf16_f32 v29, v34, v35
	global_store_dwordx4 v[2:3], v[26:29], off
	v_pk_mul_f32 v[16:17], v[30:31], v[30:31]
	v_pk_mul_f32 v[18:19], v[32:33], v[32:33]
	v_pk_mul_f32 v[20:21], v[34:35], v[34:35]
	global_load_dwordx4 v[30:33], v[0:1], off offset:528
	global_load_dwordx4 v[34:37], v[0:1], off offset:512
	v_pk_mul_f32 v[6:7], v[22:23], v[22:23]
	v_add_f32_e32 v16, v16, v17
	v_add_f32_e32 v6, v6, v7
	v_add_f32_e32 v6, v6, v16
	v_add_f32_e32 v20, v20, v21
	v_add_f32_e32 v18, v18, v19
	v_add_f32_e32 v18, v18, v20
	v_add_f32_e32 v6, v6, v18
	s_waitcnt vmcnt(2)
	v_lshlrev_b32_e32 v0, 16, v206
	v_and_b32_e32 v1, 0xffff0000, v206
	s_waitcnt vmcnt(0)
	v_pk_fma_f32 v[0:1], v[14:15], v[34:35], v[0:1]
	v_lshlrev_b32_e32 v14, 16, v207
	v_and_b32_e32 v15, 0xffff0000, v207
	v_pk_fma_f32 v[12:13], v[12:13], v[36:37], v[14:15]
	v_lshlrev_b32_e32 v14, 16, v208
	v_and_b32_e32 v15, 0xffff0000, v208
	v_pk_fma_f32 v[10:11], v[10:11], v[30:31], v[14:15]
	v_lshlrev_b32_e32 v14, 16, v209
	v_and_b32_e32 v15, 0xffff0000, v209
	v_pk_fma_f32 v[14:15], v[8:9], v[32:33], v[14:15]
	v_pk_mul_f32 v[24:25], v[10:11], v[10:11]
	v_pk_mul_f32 v[26:27], v[14:15], v[14:15]
	v_pk_mul_f32 v[8:9], v[0:1], v[0:1]
	v_pk_mul_f32 v[22:23], v[12:13], v[12:13]
	v_add_f32_e32 v7, v26, v27
	v_add_f32_e32 v16, v24, v25
	v_add_f32_e32 v7, v16, v7
	v_add_f32_e32 v16, v22, v23
	v_add_f32_e32 v8, v8, v9
	v_add_f32_e32 v8, v8, v16
	v_add_f32_e32 v7, v8, v7
	v_add_f32_e32 v16, v6, v7
	v_cvt_pk_bf16_f32 v6, v0, v1
	ds_bpermute_b32 v0, v177, v16
	v_cvt_pk_bf16_f32 v7, v12, v13
	v_cvt_pk_bf16_f32 v8, v10, v11
	v_cvt_pk_bf16_f32 v9, v14, v15
	global_store_dwordx4 v[2:3], v[6:9], off offset:256
	s_waitcnt lgkmcnt(0)
	v_add_f32_e32 v0, v16, v0
	ds_bpermute_b32 v1, v178, v0
	s_and_saveexec_b64 s[22:23], s[38:39]
	s_cbranch_execz .LBB0_442
	v_lshlrev_b64 v[2:3], 6, v[4:5]
	v_lshl_add_u64 v[2:3], s[20:21], 0, v[2:3]
	s_waitcnt lgkmcnt(0)
	v_add_f32_e32 v0, v0, v1
	global_store_dword v[2:3], v0, off
